# S5-out: epilogue loads hoisted (16 uw + 2 dsk, constant vmcnt ladder); last Toeplitz iteration peeled and its freed quads prefetch the carry part; carry part unrolled as a 27-deep register ring
# speedup vs baseline: 1.0154x; 1.0072x over previous
; #define GAS __attribute__((address_space(1)))
; #define LAS __attribute__((address_space(3)))
; __device__ __forceinline__ void ph_s5_out(Frame& F) {
;     ...
;         for (int s0 = 0; s0 < 64; s0 += 16) {
;             bf16x8_t bq[16];
; #pragma unroll
;             for (int e = 0; e < 16; ++e) bq[e] = *(const GAS bf16x8_t*)(ub + 512 * (s0 + e));
; #pragma unroll
;             for (int e = 0; e < 16; ++e) { const int sI = s0 + e; const bf16x8_t b = bq[e];
; #pragma unroll
;             for (int i = 0; i < 4; ++i) { const bf16x8_t a = *(const LAS bf16x8_t*)(tl + (16 * i - sI) * 16 * TP_PITCH); acc[i] = __builtin_amdgcn_mfma_f32_32x32x16_bf16(a, b, acc[i], 0, 0, 0); }
;             }
;         }
.LBB0_972:
	v_add_co_u32_e32 v210, vcc, 0x2000, v82
	s_nop 1
	v_addc_co_u32_e32 v211, vcc, 0, v83, vcc
	v_add_co_u32_e32 v212, vcc, 0x4000, v82
	s_nop 1
	v_addc_co_u32_e32 v213, vcc, 0, v83, vcc
	ds_read_b128 v[84:87], v68 offset:11520
	ds_read_b128 v[96:99], v68 offset:12288
	s_waitcnt vmcnt(15) lgkmcnt(1)
	v_mfma_f32_32x32x16_bf16 v[50:65], v[84:87], v[142:145], v[50:65]
	ds_read_b128 v[84:87], v68 offset:23808
	ds_read_b128 v[108:111], v68 offset:24576
	s_waitcnt lgkmcnt(1)
	v_mfma_f32_32x32x16_bf16 v[34:49], v[84:87], v[142:145], v[34:49]
	ds_read_b128 v[84:87], v68 offset:36096
	ds_read_b128 v[112:115], v68 offset:36864
	s_waitcnt lgkmcnt(1)
	v_mfma_f32_32x32x16_bf16 v[18:33], v[84:87], v[142:145], v[18:33]
	ds_read_b128 v[84:87], v68 offset:48384
	ds_read_b128 v[116:119], v68
	s_waitcnt lgkmcnt(1)
	v_mfma_f32_32x32x16_bf16 v[2:17], v[84:87], v[142:145], v[2:17]
	global_load_dwordx4 v[142:145], v[82:83], off offset:1024
	ds_read_b128 v[84:87], v68 offset:10752
	ds_read_b128 v[100:103], v68 offset:9984
	s_waitcnt vmcnt(15) lgkmcnt(1)
	v_mfma_f32_32x32x16_bf16 v[50:65], v[84:87], v[146:149], v[50:65]
	ds_read_b128 v[84:87], v68 offset:23040
	ds_read_b128 v[120:123], v68 offset:22272
	s_waitcnt lgkmcnt(1)
	v_mfma_f32_32x32x16_bf16 v[34:49], v[84:87], v[146:149], v[34:49]
	ds_read_b128 v[84:87], v68 offset:35328
	ds_read_b128 v[124:127], v68 offset:34560
	ds_read_b128 v[128:131], v68 offset:46848
	s_waitcnt lgkmcnt(2)
	v_mfma_f32_32x32x16_bf16 v[18:33], v[84:87], v[146:149], v[18:33]
	ds_read_b128 v[84:87], v68 offset:47616
	s_waitcnt lgkmcnt(0)
	v_mfma_f32_32x32x16_bf16 v[2:17], v[84:87], v[146:149], v[2:17]
	global_load_dwordx4 v[146:149], v[82:83], off offset:2048
	s_waitcnt vmcnt(15)
	v_mfma_f32_32x32x16_bf16 v[50:65], v[100:103], v[150:153], v[50:65]
	v_mfma_f32_32x32x16_bf16 v[34:49], v[120:123], v[150:153], v[34:49]
	ds_read_b128 v[100:103], v68 offset:9216
	ds_read_b128 v[120:123], v68 offset:8448
	v_mfma_f32_32x32x16_bf16 v[18:33], v[124:127], v[150:153], v[18:33]
	v_mfma_f32_32x32x16_bf16 v[2:17], v[128:131], v[150:153], v[2:17]
	global_load_dwordx4 v[150:153], v[82:83], off offset:3072
	s_waitcnt vmcnt(15) lgkmcnt(1)
	v_mfma_f32_32x32x16_bf16 v[50:65], v[100:103], v[154:157], v[50:65]
	ds_read_b128 v[100:103], v68 offset:21504
	ds_read_b128 v[128:131], v68 offset:20736
	s_waitcnt lgkmcnt(1)
	v_mfma_f32_32x32x16_bf16 v[34:49], v[100:103], v[154:157], v[34:49]
	ds_read_b128 v[100:103], v68 offset:33792
	ds_read_b128 v[132:135], v68 offset:33024
	s_waitcnt lgkmcnt(1)
	v_mfma_f32_32x32x16_bf16 v[18:33], v[100:103], v[154:157], v[18:33]
	ds_read_b128 v[100:103], v68 offset:46080
	ds_read_b128 v[136:139], v68 offset:45312
	s_waitcnt lgkmcnt(1)
	v_mfma_f32_32x32x16_bf16 v[2:17], v[100:103], v[154:157], v[2:17]
	global_load_dwordx4 v[154:157], v[210:211], off offset:-4096
	s_waitcnt vmcnt(15)
	v_mfma_f32_32x32x16_bf16 v[50:65], v[120:123], v[158:161], v[50:65]
	ds_read_b128 v[100:103], v68 offset:7680
	ds_read_b128 v[120:123], v68 offset:6912
	v_mfma_f32_32x32x16_bf16 v[34:49], v[128:131], v[158:161], v[34:49]
	v_mfma_f32_32x32x16_bf16 v[18:33], v[132:135], v[158:161], v[18:33]
	s_waitcnt lgkmcnt(2)
	v_mfma_f32_32x32x16_bf16 v[2:17], v[136:139], v[158:161], v[2:17]
	global_load_dwordx4 v[158:161], v[210:211], off offset:-3072
	s_waitcnt vmcnt(15) lgkmcnt(1)
	v_mfma_f32_32x32x16_bf16 v[50:65], v[100:103], v[162:165], v[50:65]
	ds_read_b128 v[100:103], v68 offset:19968
	ds_read_b128 v[128:131], v68 offset:19200
	s_waitcnt lgkmcnt(1)
	v_mfma_f32_32x32x16_bf16 v[34:49], v[100:103], v[162:165], v[34:49]
	ds_read_b128 v[100:103], v68 offset:32256
	ds_read_b128 v[132:135], v68 offset:31488
	s_waitcnt lgkmcnt(1)
	v_mfma_f32_32x32x16_bf16 v[18:33], v[100:103], v[162:165], v[18:33]
	ds_read_b128 v[100:103], v68 offset:44544
	ds_read_b128 v[136:139], v68 offset:43776
	s_waitcnt lgkmcnt(1)
	v_mfma_f32_32x32x16_bf16 v[2:17], v[100:103], v[162:165], v[2:17]
	global_load_dwordx4 v[162:165], v[210:211], off offset:-2048
	s_waitcnt vmcnt(15)
	v_mfma_f32_32x32x16_bf16 v[50:65], v[120:123], v[166:169], v[50:65]
	ds_read_b128 v[100:103], v68 offset:6144
	ds_read_b128 v[120:123], v68 offset:5376
	v_mfma_f32_32x32x16_bf16 v[34:49], v[128:131], v[166:169], v[34:49]
	v_mfma_f32_32x32x16_bf16 v[18:33], v[132:135], v[166:169], v[18:33]
	s_waitcnt lgkmcnt(2)
	v_mfma_f32_32x32x16_bf16 v[2:17], v[136:139], v[166:169], v[2:17]
	global_load_dwordx4 v[166:169], v[210:211], off offset:-1024
	s_waitcnt vmcnt(15) lgkmcnt(1)
	v_mfma_f32_32x32x16_bf16 v[50:65], v[100:103], v[170:173], v[50:65]
	ds_read_b128 v[100:103], v68 offset:18432
	ds_read_b128 v[124:127], v68 offset:17664
	s_waitcnt lgkmcnt(1)
	v_mfma_f32_32x32x16_bf16 v[34:49], v[100:103], v[170:173], v[34:49]
	ds_read_b128 v[100:103], v68 offset:30720
	ds_read_b128 v[128:131], v68 offset:29952
	s_waitcnt lgkmcnt(1)
	v_mfma_f32_32x32x16_bf16 v[18:33], v[100:103], v[170:173], v[18:33]
	ds_read_b128 v[100:103], v68 offset:43008
	ds_read_b128 v[132:135], v68 offset:42240
	s_waitcnt lgkmcnt(1)
	v_mfma_f32_32x32x16_bf16 v[2:17], v[100:103], v[170:173], v[2:17]
	global_load_dwordx4 v[170:173], v[210:211], off offset:0
	ds_read_b128 v[84:87], v68 offset:4608
	ds_read_b128 v[100:103], v68 offset:3840
	s_waitcnt vmcnt(15)
	v_mfma_f32_32x32x16_bf16 v[50:65], v[120:123], v[174:177], v[50:65]
	v_mfma_f32_32x32x16_bf16 v[34:49], v[124:127], v[174:177], v[34:49]
	v_mfma_f32_32x32x16_bf16 v[18:33], v[128:131], v[174:177], v[18:33]
	s_waitcnt lgkmcnt(2)
	v_mfma_f32_32x32x16_bf16 v[2:17], v[132:135], v[174:177], v[2:17]
	global_load_dwordx4 v[174:177], v[210:211], off offset:1024
	s_waitcnt vmcnt(15) lgkmcnt(1)
; #define GAS __attribute__((address_space(1)))
; #define LAS __attribute__((address_space(3)))
; __device__ __forceinline__ void ph_s5_out(Frame& F) {
;     ...
;         for (int s0 = 0; s0 < 64; s0 += 16) {
;             bf16x8_t bq[16];
; #pragma unroll
;             for (int e = 0; e < 16; ++e) bq[e] = *(const GAS bf16x8_t*)(ub + 512 * (s0 + e));
; #pragma unroll
;             for (int e = 0; e < 16; ++e) { const int sI = s0 + e; const bf16x8_t b = bq[e];
; #pragma unroll
;             for (int i = 0; i < 4; ++i) { const bf16x8_t a = *(const LAS bf16x8_t*)(tl + (16 * i - sI) * 16 * TP_PITCH); acc[i] = __builtin_amdgcn_mfma_f32_32x32x16_bf16(a, b, acc[i], 0, 0, 0); }
;             }
;         }
;         { const bf16* sb = (const bf16*)(ws + WS_SIN) + (size_t)g * 9 * 16 * 512 + ((size_t)nb * 16 * 64 + lane) * 8;
;           const bf16* wc = (const bf16*)(ws + WS_WC) + (size_t)g * 1024 * 256 + (((size_t)wave * 16) * 64 + lane) * 8;
; #pragma unroll 4
;           for (int kk = 0; kk < 16; ++kk) {
;               const bf16x8_t b = *(const GAS bf16x8_t*)(sb + 512 * kk);
; #pragma unroll
;               for (int i = 0; i < 4; ++i) { const bf16x8_t a = *(const GAS bf16x8_t*)(wc + (size_t)(8 * i) * 16 * 512 + 512 * kk); acc[i] = __builtin_amdgcn_mfma_f32_32x32x16_bf16(a, b, acc[i], 0, 0, 0); }
;           } }
	v_mfma_f32_32x32x16_bf16 v[50:65], v[84:87], v[178:181], v[50:65]
	ds_read_b128 v[84:87], v68 offset:16896
	ds_read_b128 v[124:127], v68 offset:16128
	s_waitcnt lgkmcnt(1)
	v_mfma_f32_32x32x16_bf16 v[34:49], v[84:87], v[178:181], v[34:49]
	ds_read_b128 v[84:87], v68 offset:29184
	ds_read_b128 v[128:131], v68 offset:28416
	s_waitcnt lgkmcnt(1)
	v_mfma_f32_32x32x16_bf16 v[18:33], v[84:87], v[178:181], v[18:33]
	ds_read_b128 v[84:87], v68 offset:41472
	ds_read_b128 v[132:135], v68 offset:40704
	s_waitcnt lgkmcnt(1)
	v_mfma_f32_32x32x16_bf16 v[2:17], v[84:87], v[178:181], v[2:17]
	global_load_dwordx4 v[178:181], v[210:211], off offset:2048
	s_waitcnt vmcnt(15)
	v_mfma_f32_32x32x16_bf16 v[50:65], v[100:103], v[182:185], v[50:65]
	v_mfma_f32_32x32x16_bf16 v[34:49], v[124:127], v[182:185], v[34:49]
	v_mfma_f32_32x32x16_bf16 v[18:33], v[128:131], v[182:185], v[18:33]
	s_waitcnt lgkmcnt(0)
	v_mfma_f32_32x32x16_bf16 v[2:17], v[132:135], v[182:185], v[2:17]
	global_load_dwordx4 v[182:185], v[210:211], off offset:3072
	ds_read_b128 v[104:107], v68 offset:3072
	ds_read_b128 v[120:123], v68 offset:2304
	s_waitcnt vmcnt(15) lgkmcnt(1)
	v_mfma_f32_32x32x16_bf16 v[50:65], v[104:107], v[190:193], v[50:65]
	ds_read_b128 v[104:107], v68 offset:15360
	ds_read_b128 v[124:127], v68 offset:14592
	s_waitcnt lgkmcnt(1)
	v_mfma_f32_32x32x16_bf16 v[34:49], v[104:107], v[190:193], v[34:49]
	ds_read_b128 v[104:107], v68 offset:27648
	ds_read_b128 v[128:131], v68 offset:26880
	s_waitcnt lgkmcnt(1)
	v_mfma_f32_32x32x16_bf16 v[18:33], v[104:107], v[190:193], v[18:33]
	ds_read_b128 v[104:107], v68 offset:39936
	ds_read_b128 v[132:135], v68 offset:39168
	s_waitcnt lgkmcnt(1)
	v_mfma_f32_32x32x16_bf16 v[2:17], v[104:107], v[190:193], v[2:17]
	global_load_dwordx4 v[190:193], v[212:213], off offset:-4096
	s_waitcnt vmcnt(15)
	v_mfma_f32_32x32x16_bf16 v[50:65], v[120:123], v[194:197], v[50:65]
	v_mfma_f32_32x32x16_bf16 v[34:49], v[124:127], v[194:197], v[34:49]
	v_mfma_f32_32x32x16_bf16 v[18:33], v[128:131], v[194:197], v[18:33]
	s_waitcnt lgkmcnt(0)
	v_mfma_f32_32x32x16_bf16 v[2:17], v[132:135], v[194:197], v[2:17]
	global_load_dwordx4 v[194:197], v[212:213], off offset:-3072
	ds_read_b128 v[100:103], v68 offset:1536
	ds_read_b128 v[120:123], v68 offset:768
	s_waitcnt vmcnt(15) lgkmcnt(1)
	v_mfma_f32_32x32x16_bf16 v[50:65], v[100:103], v[198:201], v[50:65]
	ds_read_b128 v[100:103], v68 offset:13824
	ds_read_b128 v[124:127], v68 offset:13056
	s_waitcnt lgkmcnt(1)
	v_mfma_f32_32x32x16_bf16 v[34:49], v[100:103], v[198:201], v[34:49]
	ds_read_b128 v[100:103], v68 offset:26112
	ds_read_b128 v[128:131], v68 offset:25344
	s_waitcnt lgkmcnt(1)
	v_mfma_f32_32x32x16_bf16 v[18:33], v[100:103], v[198:201], v[18:33]
	ds_read_b128 v[100:103], v68 offset:38400
	ds_read_b128 v[132:135], v68 offset:37632
	v_add_u32_e32 v68, 0xffffd000, v68
	s_waitcnt lgkmcnt(1)
	v_mfma_f32_32x32x16_bf16 v[2:17], v[100:103], v[198:201], v[2:17]
	global_load_dwordx4 v[198:201], v[212:213], off offset:-2048
	s_waitcnt vmcnt(15)
	v_mfma_f32_32x32x16_bf16 v[50:65], v[120:123], v[202:205], v[50:65]
	v_mfma_f32_32x32x16_bf16 v[34:49], v[124:127], v[202:205], v[34:49]
	v_mfma_f32_32x32x16_bf16 v[18:33], v[128:131], v[202:205], v[18:33]
	s_waitcnt lgkmcnt(0)
	v_mfma_f32_32x32x16_bf16 v[2:17], v[132:135], v[202:205], v[2:17]
	global_load_dwordx4 v[202:205], v[212:213], off offset:-1024
	s_waitcnt vmcnt(15)
	v_mfma_f32_32x32x16_bf16 v[50:65], v[116:119], v[206:209], v[50:65]
	v_mfma_f32_32x32x16_bf16 v[34:49], v[96:99], v[206:209], v[34:49]
	v_mfma_f32_32x32x16_bf16 v[18:33], v[108:111], v[206:209], v[18:33]
	v_mfma_f32_32x32x16_bf16 v[2:17], v[112:115], v[206:209], v[2:17]
	global_load_dwordx4 v[206:209], v[212:213], off offset:0
	v_lshl_add_u64 v[82:83], v[82:83], 0, s[22:23]
	s_add_i32 s25, s25, 16
	s_cmp_gt_u32 s25, 31
	s_cbranch_scc0 .LBB0_972
	s_ashr_i32 s25, s24, 31
	s_mul_i32 s49, s26, 0x24000
	s_lshl_b64 s[28:29], s[24:25], 14
	s_lshl_b64 s[34:35], s[26:27], 19
	s_mul_hi_i32 s31, s26, 0x24000
	s_add_u32 s28, s49, s28
	s_addc_u32 s29, s31, s29
	s_add_u32 s28, s28, 0x800
	s_addc_u32 s29, s29, 0
	s_add_u32 s34, s34, 0x9901000
	s_addc_u32 s35, s35, 0
	v_lshl_add_u64 v[88:89], v[80:81], 0, s[28:29]
	v_lshl_add_u64 v[214:215], v[78:79], 0, s[34:35]
	s_mov_b64 s[28:29], 0x20000
	v_lshl_add_u64 v[216:217], v[214:215], 0, s[28:29]
	v_lshl_add_u64 v[140:141], v[216:217], 0, s[28:29]
	v_lshl_add_u64 v[186:187], v[140:141], 0, s[28:29]
	ds_read_b128 v[84:87], v68 offset:11520
	ds_read_b128 v[96:99], v68 offset:12288
	s_waitcnt vmcnt(15) lgkmcnt(1)
	v_mfma_f32_32x32x16_bf16 v[50:65], v[84:87], v[142:145], v[50:65]
	ds_read_b128 v[84:87], v68 offset:23808
	ds_read_b128 v[108:111], v68 offset:24576
	s_waitcnt lgkmcnt(1)
	v_mfma_f32_32x32x16_bf16 v[34:49], v[84:87], v[142:145], v[34:49]
	ds_read_b128 v[84:87], v68 offset:36096
	ds_read_b128 v[112:115], v68 offset:36864
	s_waitcnt lgkmcnt(1)
	v_mfma_f32_32x32x16_bf16 v[18:33], v[84:87], v[142:145], v[18:33]
	ds_read_b128 v[84:87], v68 offset:48384
	ds_read_b128 v[116:119], v68
	s_waitcnt lgkmcnt(1)
	v_mfma_f32_32x32x16_bf16 v[2:17], v[84:87], v[142:145], v[2:17]
	global_load_dwordx4 v[142:145], v[88:89], off offset:-4096
	ds_read_b128 v[84:87], v68 offset:10752
	ds_read_b128 v[100:103], v68 offset:9984
	s_waitcnt vmcnt(15) lgkmcnt(1)
	v_mfma_f32_32x32x16_bf16 v[50:65], v[84:87], v[146:149], v[50:65]
	ds_read_b128 v[84:87], v68 offset:23040
	ds_read_b128 v[120:123], v68 offset:22272
	s_waitcnt lgkmcnt(1)
	v_mfma_f32_32x32x16_bf16 v[34:49], v[84:87], v[146:149], v[34:49]
	ds_read_b128 v[84:87], v68 offset:35328
	ds_read_b128 v[124:127], v68 offset:34560
	ds_read_b128 v[128:131], v68 offset:46848
	s_waitcnt lgkmcnt(2)
; #define GAS __attribute__((address_space(1)))
; #define LAS __attribute__((address_space(3)))
; __device__ __forceinline__ void ph_s5_out(Frame& F) {
;     ...
;         for (int s0 = 0; s0 < 64; s0 += 16) {
;             bf16x8_t bq[16];
; #pragma unroll
;             for (int e = 0; e < 16; ++e) bq[e] = *(const GAS bf16x8_t*)(ub + 512 * (s0 + e));
; #pragma unroll
;             for (int e = 0; e < 16; ++e) { const int sI = s0 + e; const bf16x8_t b = bq[e];
; #pragma unroll
;             for (int i = 0; i < 4; ++i) { const bf16x8_t a = *(const LAS bf16x8_t*)(tl + (16 * i - sI) * 16 * TP_PITCH); acc[i] = __builtin_amdgcn_mfma_f32_32x32x16_bf16(a, b, acc[i], 0, 0, 0); }
;             }
;         }
;         { const bf16* sb = (const bf16*)(ws + WS_SIN) + (size_t)g * 9 * 16 * 512 + ((size_t)nb * 16 * 64 + lane) * 8;
;           const bf16* wc = (const bf16*)(ws + WS_WC) + (size_t)g * 1024 * 256 + (((size_t)wave * 16) * 64 + lane) * 8;
; #pragma unroll 4
;           for (int kk = 0; kk < 16; ++kk) {
;               const bf16x8_t b = *(const GAS bf16x8_t*)(sb + 512 * kk);
; #pragma unroll
;               for (int i = 0; i < 4; ++i) { const bf16x8_t a = *(const GAS bf16x8_t*)(wc + (size_t)(8 * i) * 16 * 512 + 512 * kk); acc[i] = __builtin_amdgcn_mfma_f32_32x32x16_bf16(a, b, acc[i], 0, 0, 0); }
	v_mfma_f32_32x32x16_bf16 v[18:33], v[84:87], v[146:149], v[18:33]
	ds_read_b128 v[84:87], v68 offset:47616
	s_waitcnt lgkmcnt(0)
	v_mfma_f32_32x32x16_bf16 v[2:17], v[84:87], v[146:149], v[2:17]
	global_load_dwordx4 v[146:149], v[214:215], off offset:-4096
	s_waitcnt vmcnt(15)
	v_mfma_f32_32x32x16_bf16 v[50:65], v[100:103], v[150:153], v[50:65]
	v_mfma_f32_32x32x16_bf16 v[34:49], v[120:123], v[150:153], v[34:49]
	ds_read_b128 v[100:103], v68 offset:9216
	ds_read_b128 v[120:123], v68 offset:8448
	v_mfma_f32_32x32x16_bf16 v[18:33], v[124:127], v[150:153], v[18:33]
	v_mfma_f32_32x32x16_bf16 v[2:17], v[128:131], v[150:153], v[2:17]
	global_load_dwordx4 v[150:153], v[216:217], off offset:-4096
	s_waitcnt vmcnt(15) lgkmcnt(1)
	v_mfma_f32_32x32x16_bf16 v[50:65], v[100:103], v[154:157], v[50:65]
	ds_read_b128 v[100:103], v68 offset:21504
	ds_read_b128 v[128:131], v68 offset:20736
	s_waitcnt lgkmcnt(1)
	v_mfma_f32_32x32x16_bf16 v[34:49], v[100:103], v[154:157], v[34:49]
	ds_read_b128 v[100:103], v68 offset:33792
	ds_read_b128 v[132:135], v68 offset:33024
	s_waitcnt lgkmcnt(1)
	v_mfma_f32_32x32x16_bf16 v[18:33], v[100:103], v[154:157], v[18:33]
	ds_read_b128 v[100:103], v68 offset:46080
	ds_read_b128 v[136:139], v68 offset:45312
	s_waitcnt lgkmcnt(1)
	v_mfma_f32_32x32x16_bf16 v[2:17], v[100:103], v[154:157], v[2:17]
	global_load_dwordx4 v[154:157], v[140:141], off offset:-4096
	s_waitcnt vmcnt(15)
	v_mfma_f32_32x32x16_bf16 v[50:65], v[120:123], v[158:161], v[50:65]
	ds_read_b128 v[100:103], v68 offset:7680
	ds_read_b128 v[120:123], v68 offset:6912
	v_mfma_f32_32x32x16_bf16 v[34:49], v[128:131], v[158:161], v[34:49]
	v_mfma_f32_32x32x16_bf16 v[18:33], v[132:135], v[158:161], v[18:33]
	s_waitcnt lgkmcnt(2)
	v_mfma_f32_32x32x16_bf16 v[2:17], v[136:139], v[158:161], v[2:17]
	global_load_dwordx4 v[158:161], v[186:187], off offset:-4096
	s_waitcnt vmcnt(15) lgkmcnt(1)
	v_mfma_f32_32x32x16_bf16 v[50:65], v[100:103], v[162:165], v[50:65]
	ds_read_b128 v[100:103], v68 offset:19968
	ds_read_b128 v[128:131], v68 offset:19200
	s_waitcnt lgkmcnt(1)
	v_mfma_f32_32x32x16_bf16 v[34:49], v[100:103], v[162:165], v[34:49]
	ds_read_b128 v[100:103], v68 offset:32256
	ds_read_b128 v[132:135], v68 offset:31488
	s_waitcnt lgkmcnt(1)
	v_mfma_f32_32x32x16_bf16 v[18:33], v[100:103], v[162:165], v[18:33]
	ds_read_b128 v[100:103], v68 offset:44544
	ds_read_b128 v[136:139], v68 offset:43776
	s_waitcnt lgkmcnt(1)
	v_mfma_f32_32x32x16_bf16 v[2:17], v[100:103], v[162:165], v[2:17]
	global_load_dwordx4 v[162:165], v[88:89], off offset:-3072
	s_waitcnt vmcnt(15)
	v_mfma_f32_32x32x16_bf16 v[50:65], v[120:123], v[166:169], v[50:65]
	ds_read_b128 v[100:103], v68 offset:6144
	ds_read_b128 v[120:123], v68 offset:5376
	v_mfma_f32_32x32x16_bf16 v[34:49], v[128:131], v[166:169], v[34:49]
	v_mfma_f32_32x32x16_bf16 v[18:33], v[132:135], v[166:169], v[18:33]
	s_waitcnt lgkmcnt(2)
	v_mfma_f32_32x32x16_bf16 v[2:17], v[136:139], v[166:169], v[2:17]
	global_load_dwordx4 v[166:169], v[214:215], off offset:-3072
	s_waitcnt vmcnt(15) lgkmcnt(1)
	v_mfma_f32_32x32x16_bf16 v[50:65], v[100:103], v[170:173], v[50:65]
	ds_read_b128 v[100:103], v68 offset:18432
	ds_read_b128 v[124:127], v68 offset:17664
	s_waitcnt lgkmcnt(1)
	v_mfma_f32_32x32x16_bf16 v[34:49], v[100:103], v[170:173], v[34:49]
	ds_read_b128 v[100:103], v68 offset:30720
	ds_read_b128 v[128:131], v68 offset:29952
	s_waitcnt lgkmcnt(1)
	v_mfma_f32_32x32x16_bf16 v[18:33], v[100:103], v[170:173], v[18:33]
	ds_read_b128 v[100:103], v68 offset:43008
	ds_read_b128 v[132:135], v68 offset:42240
	s_waitcnt lgkmcnt(1)
	v_mfma_f32_32x32x16_bf16 v[2:17], v[100:103], v[170:173], v[2:17]
	global_load_dwordx4 v[170:173], v[216:217], off offset:-3072
	ds_read_b128 v[84:87], v68 offset:4608
	ds_read_b128 v[100:103], v68 offset:3840
	s_waitcnt vmcnt(15)
	v_mfma_f32_32x32x16_bf16 v[50:65], v[120:123], v[174:177], v[50:65]
	v_mfma_f32_32x32x16_bf16 v[34:49], v[124:127], v[174:177], v[34:49]
	v_mfma_f32_32x32x16_bf16 v[18:33], v[128:131], v[174:177], v[18:33]
	s_waitcnt lgkmcnt(2)
	v_mfma_f32_32x32x16_bf16 v[2:17], v[132:135], v[174:177], v[2:17]
	global_load_dwordx4 v[174:177], v[140:141], off offset:-3072
	s_waitcnt vmcnt(15) lgkmcnt(1)
	v_mfma_f32_32x32x16_bf16 v[50:65], v[84:87], v[178:181], v[50:65]
	ds_read_b128 v[84:87], v68 offset:16896
	ds_read_b128 v[124:127], v68 offset:16128
	s_waitcnt lgkmcnt(1)
	v_mfma_f32_32x32x16_bf16 v[34:49], v[84:87], v[178:181], v[34:49]
	ds_read_b128 v[84:87], v68 offset:29184
	ds_read_b128 v[128:131], v68 offset:28416
	s_waitcnt lgkmcnt(1)
	v_mfma_f32_32x32x16_bf16 v[18:33], v[84:87], v[178:181], v[18:33]
	ds_read_b128 v[84:87], v68 offset:41472
	ds_read_b128 v[132:135], v68 offset:40704
	s_waitcnt lgkmcnt(1)
	v_mfma_f32_32x32x16_bf16 v[2:17], v[84:87], v[178:181], v[2:17]
	global_load_dwordx4 v[178:181], v[186:187], off offset:-3072
	s_waitcnt vmcnt(15)
	v_mfma_f32_32x32x16_bf16 v[50:65], v[100:103], v[182:185], v[50:65]
	v_mfma_f32_32x32x16_bf16 v[34:49], v[124:127], v[182:185], v[34:49]
	v_mfma_f32_32x32x16_bf16 v[18:33], v[128:131], v[182:185], v[18:33]
	s_waitcnt lgkmcnt(0)
	v_mfma_f32_32x32x16_bf16 v[2:17], v[132:135], v[182:185], v[2:17]
	global_load_dwordx4 v[182:185], v[88:89], off offset:-2048
	ds_read_b128 v[104:107], v68 offset:3072
	ds_read_b128 v[120:123], v68 offset:2304
	s_waitcnt vmcnt(15) lgkmcnt(1)
	v_mfma_f32_32x32x16_bf16 v[50:65], v[104:107], v[190:193], v[50:65]
	ds_read_b128 v[104:107], v68 offset:15360
	ds_read_b128 v[124:127], v68 offset:14592
	s_waitcnt lgkmcnt(1)
	v_mfma_f32_32x32x16_bf16 v[34:49], v[104:107], v[190:193], v[34:49]
	ds_read_b128 v[104:107], v68 offset:27648
	ds_read_b128 v[128:131], v68 offset:26880
	s_waitcnt lgkmcnt(1)
; #define GAS __attribute__((address_space(1)))
; __device__ __forceinline__ void ph_s5_out(Frame& F) {
;     ...
;         { const bf16* sb = (const bf16*)(ws + WS_SIN) + (size_t)g * 9 * 16 * 512 + ((size_t)nb * 16 * 64 + lane) * 8;
;           const bf16* wc = (const bf16*)(ws + WS_WC) + (size_t)g * 1024 * 256 + (((size_t)wave * 16) * 64 + lane) * 8;
; #pragma unroll 4
;           for (int kk = 0; kk < 16; ++kk) {
;               const bf16x8_t b = *(const GAS bf16x8_t*)(sb + 512 * kk);
; #pragma unroll
;               for (int i = 0; i < 4; ++i) { const bf16x8_t a = *(const GAS bf16x8_t*)(wc + (size_t)(8 * i) * 16 * 512 + 512 * kk); acc[i] = __builtin_amdgcn_mfma_f32_32x32x16_bf16(a, b, acc[i], 0, 0, 0); }
;           } }
	v_mfma_f32_32x32x16_bf16 v[18:33], v[104:107], v[190:193], v[18:33]
	ds_read_b128 v[104:107], v68 offset:39936
	ds_read_b128 v[132:135], v68 offset:39168
	s_waitcnt lgkmcnt(1)
	v_mfma_f32_32x32x16_bf16 v[2:17], v[104:107], v[190:193], v[2:17]
	global_load_dwordx4 v[190:193], v[214:215], off offset:-2048
	s_waitcnt vmcnt(15)
	v_mfma_f32_32x32x16_bf16 v[50:65], v[120:123], v[194:197], v[50:65]
	v_mfma_f32_32x32x16_bf16 v[34:49], v[124:127], v[194:197], v[34:49]
	v_mfma_f32_32x32x16_bf16 v[18:33], v[128:131], v[194:197], v[18:33]
	s_waitcnt lgkmcnt(0)
	v_mfma_f32_32x32x16_bf16 v[2:17], v[132:135], v[194:197], v[2:17]
	global_load_dwordx4 v[194:197], v[216:217], off offset:-2048
	ds_read_b128 v[100:103], v68 offset:1536
	ds_read_b128 v[120:123], v68 offset:768
	s_waitcnt vmcnt(15) lgkmcnt(1)
	v_mfma_f32_32x32x16_bf16 v[50:65], v[100:103], v[198:201], v[50:65]
	ds_read_b128 v[100:103], v68 offset:13824
	ds_read_b128 v[124:127], v68 offset:13056
	s_waitcnt lgkmcnt(1)
	v_mfma_f32_32x32x16_bf16 v[34:49], v[100:103], v[198:201], v[34:49]
	ds_read_b128 v[100:103], v68 offset:26112
	ds_read_b128 v[128:131], v68 offset:25344
	s_waitcnt lgkmcnt(1)
	v_mfma_f32_32x32x16_bf16 v[18:33], v[100:103], v[198:201], v[18:33]
	ds_read_b128 v[100:103], v68 offset:38400
	ds_read_b128 v[132:135], v68 offset:37632
	v_add_u32_e32 v68, 0xffffd000, v68
	s_waitcnt lgkmcnt(1)
	v_mfma_f32_32x32x16_bf16 v[2:17], v[100:103], v[198:201], v[2:17]
	global_load_dwordx4 v[198:201], v[140:141], off offset:-2048
	s_waitcnt vmcnt(15)
	v_mfma_f32_32x32x16_bf16 v[50:65], v[120:123], v[202:205], v[50:65]
	v_mfma_f32_32x32x16_bf16 v[34:49], v[124:127], v[202:205], v[34:49]
	v_mfma_f32_32x32x16_bf16 v[18:33], v[128:131], v[202:205], v[18:33]
	s_waitcnt lgkmcnt(0)
	v_mfma_f32_32x32x16_bf16 v[2:17], v[132:135], v[202:205], v[2:17]
	global_load_dwordx4 v[202:205], v[186:187], off offset:-2048
	s_waitcnt vmcnt(15)
	v_mfma_f32_32x32x16_bf16 v[50:65], v[116:119], v[206:209], v[50:65]
	v_mfma_f32_32x32x16_bf16 v[34:49], v[96:99], v[206:209], v[34:49]
	v_mfma_f32_32x32x16_bf16 v[18:33], v[108:111], v[206:209], v[18:33]
	v_mfma_f32_32x32x16_bf16 v[2:17], v[112:115], v[206:209], v[2:17]
	global_load_dwordx4 v[206:209], v[88:89], off offset:-1024
	global_load_dwordx4 v[96:99], v[214:215], off offset:-1024
	global_load_dwordx4 v[100:103], v[216:217], off offset:-1024
	global_load_dwordx4 v[104:107], v[140:141], off offset:-1024
	global_load_dwordx4 v[108:111], v[186:187], off offset:-1024
	global_load_dwordx4 v[112:115], v[88:89], off
	global_load_dwordx4 v[116:119], v[214:215], off
	global_load_dwordx4 v[120:123], v[216:217], off
	global_load_dwordx4 v[124:127], v[140:141], off
	global_load_dwordx4 v[128:131], v[186:187], off
	global_load_dwordx4 v[132:135], v[88:89], off offset:1024
	global_load_dwordx4 v[136:139], v[214:215], off offset:1024
	s_waitcnt vmcnt(25)
	v_mfma_f32_32x32x16_bf16 v[50:65], v[146:149], v[142:145], v[50:65]
	global_load_dwordx4 v[146:149], v[216:217], off offset:1024
	s_waitcnt vmcnt(25)
	v_mfma_f32_32x32x16_bf16 v[34:49], v[150:153], v[142:145], v[34:49]
	global_load_dwordx4 v[150:153], v[140:141], off offset:1024
	s_waitcnt vmcnt(25)
	v_mfma_f32_32x32x16_bf16 v[18:33], v[154:157], v[142:145], v[18:33]
	global_load_dwordx4 v[154:157], v[186:187], off offset:1024
	s_waitcnt vmcnt(25)
	v_mfma_f32_32x32x16_bf16 v[2:17], v[158:161], v[142:145], v[2:17]
	global_load_dwordx4 v[158:161], v[88:89], off offset:2048
	global_load_dwordx4 v[142:145], v[214:215], off offset:2048
	s_waitcnt vmcnt(25)
	v_mfma_f32_32x32x16_bf16 v[50:65], v[166:169], v[162:165], v[50:65]
	global_load_dwordx4 v[166:169], v[216:217], off offset:2048
	s_waitcnt vmcnt(25)
	v_mfma_f32_32x32x16_bf16 v[34:49], v[170:173], v[162:165], v[34:49]
	global_load_dwordx4 v[170:173], v[140:141], off offset:2048
	s_waitcnt vmcnt(25)
	v_mfma_f32_32x32x16_bf16 v[18:33], v[174:177], v[162:165], v[18:33]
	global_load_dwordx4 v[174:177], v[186:187], off offset:2048
	s_waitcnt vmcnt(25)
	v_mfma_f32_32x32x16_bf16 v[2:17], v[178:181], v[162:165], v[2:17]
	global_load_dwordx4 v[178:181], v[88:89], off offset:3072
	global_load_dwordx4 v[162:165], v[214:215], off offset:3072
	s_waitcnt vmcnt(25)
	v_mfma_f32_32x32x16_bf16 v[50:65], v[190:193], v[182:185], v[50:65]
	global_load_dwordx4 v[190:193], v[216:217], off offset:3072
	s_waitcnt vmcnt(25)
	v_mfma_f32_32x32x16_bf16 v[34:49], v[194:197], v[182:185], v[34:49]
	global_load_dwordx4 v[194:197], v[140:141], off offset:3072
	s_waitcnt vmcnt(25)
	v_mfma_f32_32x32x16_bf16 v[18:33], v[198:201], v[182:185], v[18:33]
	global_load_dwordx4 v[198:201], v[186:187], off offset:3072
	s_waitcnt vmcnt(25)
	v_mfma_f32_32x32x16_bf16 v[2:17], v[202:205], v[182:185], v[2:17]
	v_lshl_add_u64 v[88:89], v[88:89], 0, s[20:21]
	v_lshl_add_u64 v[214:215], v[214:215], 0, s[20:21]
	v_lshl_add_u64 v[216:217], v[216:217], 0, s[20:21]
	v_lshl_add_u64 v[140:141], v[140:141], 0, s[20:21]
	v_lshl_add_u64 v[186:187], v[186:187], 0, s[20:21]
	global_load_dwordx4 v[202:205], v[88:89], off offset:-4096
	global_load_dwordx4 v[182:185], v[214:215], off offset:-4096
	s_waitcnt vmcnt(25)
	v_mfma_f32_32x32x16_bf16 v[50:65], v[96:99], v[206:209], v[50:65]
	global_load_dwordx4 v[96:99], v[216:217], off offset:-4096
	s_waitcnt vmcnt(25)
	v_mfma_f32_32x32x16_bf16 v[34:49], v[100:103], v[206:209], v[34:49]
	global_load_dwordx4 v[100:103], v[140:141], off offset:-4096
	s_waitcnt vmcnt(25)
	v_mfma_f32_32x32x16_bf16 v[18:33], v[104:107], v[206:209], v[18:33]
	global_load_dwordx4 v[104:107], v[186:187], off offset:-4096
	s_waitcnt vmcnt(25)
; #define GAS __attribute__((address_space(1)))
; __device__ __forceinline__ void ph_s5_out(Frame& F) {
;     ...
;         { const bf16* sb = (const bf16*)(ws + WS_SIN) + (size_t)g * 9 * 16 * 512 + ((size_t)nb * 16 * 64 + lane) * 8;
;           const bf16* wc = (const bf16*)(ws + WS_WC) + (size_t)g * 1024 * 256 + (((size_t)wave * 16) * 64 + lane) * 8;
; #pragma unroll 4
;           for (int kk = 0; kk < 16; ++kk) {
;               const bf16x8_t b = *(const GAS bf16x8_t*)(sb + 512 * kk);
; #pragma unroll
;               for (int i = 0; i < 4; ++i) { const bf16x8_t a = *(const GAS bf16x8_t*)(wc + (size_t)(8 * i) * 16 * 512 + 512 * kk); acc[i] = __builtin_amdgcn_mfma_f32_32x32x16_bf16(a, b, acc[i], 0, 0, 0); }
;           } }
;         if (valid) {
	v_mfma_f32_32x32x16_bf16 v[2:17], v[108:111], v[206:209], v[2:17]
	global_load_dwordx4 v[108:111], v[88:89], off offset:-3072
	global_load_dwordx4 v[206:209], v[214:215], off offset:-3072
	s_waitcnt vmcnt(25)
	v_mfma_f32_32x32x16_bf16 v[50:65], v[116:119], v[112:115], v[50:65]
	global_load_dwordx4 v[116:119], v[216:217], off offset:-3072
	s_waitcnt vmcnt(25)
	v_mfma_f32_32x32x16_bf16 v[34:49], v[120:123], v[112:115], v[34:49]
	global_load_dwordx4 v[120:123], v[140:141], off offset:-3072
	s_waitcnt vmcnt(25)
	v_mfma_f32_32x32x16_bf16 v[18:33], v[124:127], v[112:115], v[18:33]
	global_load_dwordx4 v[124:127], v[186:187], off offset:-3072
	s_waitcnt vmcnt(25)
	v_mfma_f32_32x32x16_bf16 v[2:17], v[128:131], v[112:115], v[2:17]
	global_load_dwordx4 v[128:131], v[88:89], off offset:-2048
	global_load_dwordx4 v[112:115], v[214:215], off offset:-2048
	s_waitcnt vmcnt(25)
	v_mfma_f32_32x32x16_bf16 v[50:65], v[136:139], v[132:135], v[50:65]
	global_load_dwordx4 v[136:139], v[216:217], off offset:-2048
	s_waitcnt vmcnt(25)
	v_mfma_f32_32x32x16_bf16 v[34:49], v[146:149], v[132:135], v[34:49]
	global_load_dwordx4 v[146:149], v[140:141], off offset:-2048
	s_waitcnt vmcnt(25)
	v_mfma_f32_32x32x16_bf16 v[18:33], v[150:153], v[132:135], v[18:33]
	global_load_dwordx4 v[150:153], v[186:187], off offset:-2048
	s_waitcnt vmcnt(25)
	v_mfma_f32_32x32x16_bf16 v[2:17], v[154:157], v[132:135], v[2:17]
	global_load_dwordx4 v[154:157], v[88:89], off offset:-1024
	global_load_dwordx4 v[132:135], v[214:215], off offset:-1024
	s_waitcnt vmcnt(25)
	v_mfma_f32_32x32x16_bf16 v[50:65], v[142:145], v[158:161], v[50:65]
	global_load_dwordx4 v[142:145], v[216:217], off offset:-1024
	s_waitcnt vmcnt(25)
	v_mfma_f32_32x32x16_bf16 v[34:49], v[166:169], v[158:161], v[34:49]
	global_load_dwordx4 v[166:169], v[140:141], off offset:-1024
	s_waitcnt vmcnt(25)
	v_mfma_f32_32x32x16_bf16 v[18:33], v[170:173], v[158:161], v[18:33]
	global_load_dwordx4 v[170:173], v[186:187], off offset:-1024
	s_waitcnt vmcnt(25)
	v_mfma_f32_32x32x16_bf16 v[2:17], v[174:177], v[158:161], v[2:17]
	global_load_dwordx4 v[174:177], v[88:89], off
	global_load_dwordx4 v[158:161], v[214:215], off
	s_waitcnt vmcnt(25)
	v_mfma_f32_32x32x16_bf16 v[50:65], v[162:165], v[178:181], v[50:65]
	global_load_dwordx4 v[162:165], v[216:217], off
	s_waitcnt vmcnt(25)
	v_mfma_f32_32x32x16_bf16 v[34:49], v[190:193], v[178:181], v[34:49]
	global_load_dwordx4 v[190:193], v[140:141], off
	s_waitcnt vmcnt(25)
	v_mfma_f32_32x32x16_bf16 v[18:33], v[194:197], v[178:181], v[18:33]
	global_load_dwordx4 v[194:197], v[186:187], off
	s_waitcnt vmcnt(25)
	v_mfma_f32_32x32x16_bf16 v[2:17], v[198:201], v[178:181], v[2:17]
	global_load_dwordx4 v[198:201], v[88:89], off offset:1024
	global_load_dwordx4 v[178:181], v[214:215], off offset:1024
	s_waitcnt vmcnt(25)
	v_mfma_f32_32x32x16_bf16 v[50:65], v[182:185], v[202:205], v[50:65]
	global_load_dwordx4 v[182:185], v[216:217], off offset:1024
	s_waitcnt vmcnt(25)
	v_mfma_f32_32x32x16_bf16 v[34:49], v[96:99], v[202:205], v[34:49]
	global_load_dwordx4 v[96:99], v[140:141], off offset:1024
	s_waitcnt vmcnt(25)
	v_mfma_f32_32x32x16_bf16 v[18:33], v[100:103], v[202:205], v[18:33]
	global_load_dwordx4 v[100:103], v[186:187], off offset:1024
	s_waitcnt vmcnt(25)
	v_mfma_f32_32x32x16_bf16 v[2:17], v[104:107], v[202:205], v[2:17]
	global_load_dwordx4 v[104:107], v[88:89], off offset:2048
	global_load_dwordx4 v[202:205], v[214:215], off offset:2048
	s_waitcnt vmcnt(25)
	v_mfma_f32_32x32x16_bf16 v[50:65], v[206:209], v[108:111], v[50:65]
	global_load_dwordx4 v[206:209], v[216:217], off offset:2048
	s_waitcnt vmcnt(25)
	v_mfma_f32_32x32x16_bf16 v[34:49], v[116:119], v[108:111], v[34:49]
	global_load_dwordx4 v[116:119], v[140:141], off offset:2048
	s_waitcnt vmcnt(25)
	v_mfma_f32_32x32x16_bf16 v[18:33], v[120:123], v[108:111], v[18:33]
	global_load_dwordx4 v[120:123], v[186:187], off offset:2048
	s_waitcnt vmcnt(25)
	v_mfma_f32_32x32x16_bf16 v[2:17], v[124:127], v[108:111], v[2:17]
	global_load_dwordx4 v[124:127], v[88:89], off offset:3072
	global_load_dwordx4 v[108:111], v[214:215], off offset:3072
	s_waitcnt vmcnt(25)
	v_mfma_f32_32x32x16_bf16 v[50:65], v[112:115], v[128:131], v[50:65]
	global_load_dwordx4 v[112:115], v[216:217], off offset:3072
	s_waitcnt vmcnt(25)
	v_mfma_f32_32x32x16_bf16 v[34:49], v[136:139], v[128:131], v[34:49]
	global_load_dwordx4 v[136:139], v[140:141], off offset:3072
	s_waitcnt vmcnt(25)
	v_mfma_f32_32x32x16_bf16 v[18:33], v[146:149], v[128:131], v[18:33]
	global_load_dwordx4 v[146:149], v[186:187], off offset:3072
	s_waitcnt vmcnt(25)
	v_mfma_f32_32x32x16_bf16 v[2:17], v[150:153], v[128:131], v[2:17]
	s_waitcnt vmcnt(23)
	v_mfma_f32_32x32x16_bf16 v[50:65], v[132:135], v[154:157], v[50:65]
	s_waitcnt vmcnt(22)
	v_mfma_f32_32x32x16_bf16 v[34:49], v[142:145], v[154:157], v[34:49]
	s_waitcnt vmcnt(21)
	v_mfma_f32_32x32x16_bf16 v[18:33], v[166:169], v[154:157], v[18:33]
	s_waitcnt vmcnt(20)
	v_mfma_f32_32x32x16_bf16 v[2:17], v[170:173], v[154:157], v[2:17]
	s_waitcnt vmcnt(18)
	v_mfma_f32_32x32x16_bf16 v[50:65], v[158:161], v[174:177], v[50:65]
	s_waitcnt vmcnt(17)
	v_mfma_f32_32x32x16_bf16 v[34:49], v[162:165], v[174:177], v[34:49]
	s_waitcnt vmcnt(16)
	v_mfma_f32_32x32x16_bf16 v[18:33], v[190:193], v[174:177], v[18:33]
	s_waitcnt vmcnt(15)
	v_mfma_f32_32x32x16_bf16 v[2:17], v[194:197], v[174:177], v[2:17]
	s_waitcnt vmcnt(13)
	v_mfma_f32_32x32x16_bf16 v[50:65], v[178:181], v[198:201], v[50:65]
	s_waitcnt vmcnt(12)
	v_mfma_f32_32x32x16_bf16 v[34:49], v[182:185], v[198:201], v[34:49]
	s_waitcnt vmcnt(11)
	v_mfma_f32_32x32x16_bf16 v[18:33], v[96:99], v[198:201], v[18:33]
	s_waitcnt vmcnt(10)
	v_mfma_f32_32x32x16_bf16 v[2:17], v[100:103], v[198:201], v[2:17]
	s_waitcnt vmcnt(8)
	v_mfma_f32_32x32x16_bf16 v[50:65], v[202:205], v[104:107], v[50:65]
	s_waitcnt vmcnt(7)
	v_mfma_f32_32x32x16_bf16 v[34:49], v[206:209], v[104:107], v[34:49]
	s_waitcnt vmcnt(6)
	v_mfma_f32_32x32x16_bf16 v[18:33], v[116:119], v[104:107], v[18:33]
	s_waitcnt vmcnt(5)
	v_mfma_f32_32x32x16_bf16 v[2:17], v[120:123], v[104:107], v[2:17]
	s_waitcnt vmcnt(3)
	v_mfma_f32_32x32x16_bf16 v[50:65], v[108:111], v[124:127], v[50:65]
	s_waitcnt vmcnt(2)
	v_mfma_f32_32x32x16_bf16 v[34:49], v[112:115], v[124:127], v[34:49]
	s_waitcnt vmcnt(1)
	v_mfma_f32_32x32x16_bf16 v[18:33], v[136:139], v[124:127], v[18:33]
	s_waitcnt vmcnt(0)
	v_mfma_f32_32x32x16_bf16 v[2:17], v[146:149], v[124:127], v[2:17]
	v_lshl_or_b32 v82, s24, 5, v1
	v_cmp_gt_i32_e32 vcc, s45, v82
	s_and_saveexec_b64 s[24:25], vcc
	s_cbranch_execz .LBB0_963
; #define GAS __attribute__((address_space(1)))
; __device__ __forceinline__ unsigned pk2(float lo, float hi) { const f32x2cv v = {lo, hi}; return __builtin_bit_cast(unsigned, __builtin_convertvector(v, bf16x2cv)); }
; __device__ __forceinline__ float gelu_tanh(float x) { const float u = 0.7978845608028654f * (x + 0.044715f * x * x * x); return x * __builtin_amdgcn_rcpf(1.0f + __builtin_amdgcn_exp2f(-2.8853900817779268f * u)); }
; __device__ __forceinline__ void ph_s5_out(Frame& F) {
;     ...
;         if (valid) {
;             const float* dsk = inp(F, 24) + 16 * g;
; #pragma unroll
;             for (int i = 0; i < 4; ++i)
; #pragma unroll
;                 for (int k = 0; k < 4; ++k) { const int tloc = 2 * (wave + 8 * i) + (k >> 1), p0 = 8 * (k & 1) + 4 * hh; const size_t m = (size_t)chunk * 64 + tloc;
;                     const v2u uw = *(const GAS v2u*)((chunk < 256 ? (const bf16*)(ws + WS_UG) : (const bf16*)(ws + WS_UGC)) + ug_index(g, (int)m, p0));
;                     const float y0 = gelu_tanh(acc[i][4 * k] + dsk[p0] * bflo(uw.x)), y1 = gelu_tanh(acc[i][4 * k + 1] + dsk[p0 + 1] * bfhi(uw.x));
;                     const float y2 = gelu_tanh(acc[i][4 * k + 2] + dsk[p0 + 2] * bflo(uw.y)), y3 = gelu_tanh(acc[i][4 * k + 3] + dsk[p0 + 3] * bfhi(uw.y));
;                     v2u zw; zw.x = pk2(y0, y1); zw.y = pk2(y2, y3);
;                     *(GAS v2u*)((bf16*)(ws + WS_Z) + m * 512 + 16 * g + p0) = zw; }
	v_mov_b32_e32 v68, s46
	ds_read_b64 v[84:85], v68
	v_ashrrev_i32_e32 v83, 31, v82
	v_lshlrev_b64 v[88:89], 6, v[82:83]
	v_cmp_gt_i32_e32 vcc, s47, v82
	v_lshl_add_u64 v[102:103], v[88:89], 0, s[4:5]
	v_ashrrev_i32_e32 v83, 11, v102
	v_cndmask_b32_e32 v68, v94, v95, vcc
	v_lshl_add_u64 v[86:87], v[70:71], 0, v[68:69]
	v_ashrrev_i32_e32 v68, 6, v102
	v_add_u32_e32 v83, s30, v83
	v_mov_b32_e32 v96, s26
	v_cmp_gt_i32_e32 vcc, s47, v68
	s_lshl_b32 s28, s26, 4
	s_waitcnt lgkmcnt(0)
	v_readfirstlane_b32 s27, v84
	v_and_b32_e32 v97, 31, v68
	v_cndmask_b32_e32 v84, v96, v83, vcc
	s_ashr_i32 s29, s28, 31
	v_readfirstlane_b32 s31, v85
	v_or_b32_e32 v82, v97, v67
	v_ashrrev_i32_e32 v85, 31, v84
	v_lshlrev_b32_e32 v68, 6, v102
	s_lshl_b64 s[34:35], s[28:29], 2
	v_and_b32_e32 v68, 0xf80, v68
	v_ashrrev_i32_e32 v83, 31, v82
	v_lshlrev_b64 v[84:85], 16, v[84:85]
	v_lshl_add_u64 v[82:83], v[68:69], 0, v[82:83]
	v_lshl_add_u64 v[104:105], v[86:87], 0, v[84:85]
	s_add_u32 s26, s27, s34
	v_lshl_add_u64 v[82:83], v[82:83], 4, v[104:105]
	s_addc_u32 s27, s31, s35
	v_lshl_add_u64 v[98:99], v[188:189], 2, s[26:27]
	global_load_dwordx4 v[174:177], v[98:99], off
	global_load_dwordx4 v[178:181], v[98:99], off offset:32
	global_load_dwordx2 v[142:143], v[82:83], off
	global_load_dwordx2 v[144:145], v[82:83], off offset:512
	global_load_dwordx2 v[146:147], v[82:83], off offset:1024
	global_load_dwordx2 v[148:149], v[82:83], off offset:1536
	v_lshl_add_u64 v[82:83], v[82:83], 0, s[22:23]
	global_load_dwordx2 v[150:151], v[82:83], off
	global_load_dwordx2 v[152:153], v[82:83], off offset:512
	global_load_dwordx2 v[154:155], v[82:83], off offset:1024
	global_load_dwordx2 v[156:157], v[82:83], off offset:1536
	v_lshl_add_u64 v[82:83], v[82:83], 0, s[22:23]
	global_load_dwordx2 v[158:159], v[82:83], off
	global_load_dwordx2 v[160:161], v[82:83], off offset:512
	global_load_dwordx2 v[162:163], v[82:83], off offset:1024
	global_load_dwordx2 v[164:165], v[82:83], off offset:1536
	v_lshl_add_u64 v[82:83], v[82:83], 0, s[22:23]
	global_load_dwordx2 v[166:167], v[82:83], off
	global_load_dwordx2 v[168:169], v[82:83], off offset:512
	global_load_dwordx2 v[170:171], v[82:83], off offset:1024
	global_load_dwordx2 v[172:173], v[82:83], off offset:1536
	s_lshl_b64 s[26:27], s[28:29], 1
	s_add_u32 s26, s38, s26
	v_lshlrev_b64 v[102:103], 10, v[102:103]
	s_addc_u32 s27, s39, s27
	v_lshlrev_b64 v[84:85], 1, v[188:189]
	v_lshl_add_u64 v[102:103], s[26:27], 0, v[102:103]
	v_lshl_add_u64 v[102:103], v[102:103], 0, v[84:85]
	s_waitcnt vmcnt(15)
	v_lshlrev_b32_e32 v182, 16, v142
	v_and_b32_e32 v183, 0xffff0000, v142
	v_lshlrev_b32_e32 v184, 16, v143
	v_and_b32_e32 v185, 0xffff0000, v143
	v_pk_fma_f32 v[194:195], v[174:175], v[182:183], v[50:51]
	v_pk_fma_f32 v[196:197], v[176:177], v[184:185], v[52:53]
	v_mul_f32_e32 v190, 0x3d372713, v194
	v_mul_f32_e32 v191, 0x3d372713, v195
	v_mul_f32_e32 v192, 0x3d372713, v196
	v_mul_f32_e32 v193, 0x3d372713, v197
	v_mul_f32_e32 v190, v194, v190
	v_mul_f32_e32 v191, v195, v191
	v_mul_f32_e32 v192, v196, v192
	v_mul_f32_e32 v193, v197, v193
	v_fma_f32 v190, v194, v190, v194
	v_fma_f32 v191, v195, v191, v195
	v_fma_f32 v192, v196, v192, v196
	v_fma_f32 v193, v197, v193, v197
	v_mul_f32_e32 v190, 0x3f4c422a, v190
	v_mul_f32_e32 v191, 0x3f4c422a, v191
	v_mul_f32_e32 v192, 0x3f4c422a, v192
	v_mul_f32_e32 v193, 0x3f4c422a, v193
	v_mul_f32_e32 v190, 0xc038aa3b, v190
	v_mul_f32_e32 v191, 0xc038aa3b, v191
	v_mul_f32_e32 v192, 0xc038aa3b, v192
	v_mul_f32_e32 v193, 0xc038aa3b, v193
	v_exp_f32_e32 v190, v190
	v_exp_f32_e32 v191, v191
	v_exp_f32_e32 v192, v192
	v_exp_f32_e32 v193, v193
	v_add_f32_e32 v190, 1.0, v190
	v_add_f32_e32 v191, 1.0, v191
	v_add_f32_e32 v192, 1.0, v192
	v_add_f32_e32 v193, 1.0, v193
	v_rcp_f32_e32 v190, v190
	v_rcp_f32_e32 v191, v191
	v_rcp_f32_e32 v192, v192
	v_rcp_f32_e32 v193, v193
	v_pk_mul_f32 v[194:195], v[194:195], v[190:191]
	v_pk_mul_f32 v[196:197], v[196:197], v[192:193]
	v_cvt_pk_bf16_f32 v194, v194, v195
	v_cvt_pk_bf16_f32 v195, v196, v197
	global_store_dwordx2 v[102:103], v[194:195], off
	s_waitcnt vmcnt(15)
	v_lshlrev_b32_e32 v182, 16, v144
	v_and_b32_e32 v183, 0xffff0000, v144
	v_lshlrev_b32_e32 v184, 16, v145
	v_and_b32_e32 v185, 0xffff0000, v145
	v_pk_fma_f32 v[194:195], v[178:179], v[182:183], v[54:55]
	v_pk_fma_f32 v[196:197], v[180:181], v[184:185], v[56:57]
	v_mul_f32_e32 v190, 0x3d372713, v194
	v_mul_f32_e32 v191, 0x3d372713, v195
	v_mul_f32_e32 v192, 0x3d372713, v196
	v_mul_f32_e32 v193, 0x3d372713, v197
	v_mul_f32_e32 v190, v194, v190
	v_mul_f32_e32 v191, v195, v191
	v_mul_f32_e32 v192, v196, v192
	v_mul_f32_e32 v193, v197, v193
	v_fma_f32 v190, v194, v190, v194
	v_fma_f32 v191, v195, v191, v195
	v_fma_f32 v192, v196, v192, v196
	v_fma_f32 v193, v197, v193, v197
	v_mul_f32_e32 v190, 0x3f4c422a, v190
	v_mul_f32_e32 v191, 0x3f4c422a, v191
	v_mul_f32_e32 v192, 0x3f4c422a, v192
	v_mul_f32_e32 v193, 0x3f4c422a, v193
	v_mul_f32_e32 v190, 0xc038aa3b, v190
	v_mul_f32_e32 v191, 0xc038aa3b, v191
	v_mul_f32_e32 v192, 0xc038aa3b, v192
	v_mul_f32_e32 v193, 0xc038aa3b, v193
	v_exp_f32_e32 v190, v190
	v_exp_f32_e32 v191, v191
	v_exp_f32_e32 v192, v192
	v_exp_f32_e32 v193, v193
	v_add_f32_e32 v190, 1.0, v190
	v_add_f32_e32 v191, 1.0, v191
	v_add_f32_e32 v192, 1.0, v192
	v_add_f32_e32 v193, 1.0, v193
	v_rcp_f32_e32 v190, v190
	v_rcp_f32_e32 v191, v191
	v_rcp_f32_e32 v192, v192
	v_rcp_f32_e32 v193, v193
	v_pk_mul_f32 v[194:195], v[194:195], v[190:191]
	v_pk_mul_f32 v[196:197], v[196:197], v[192:193]
	v_cvt_pk_bf16_f32 v194, v194, v195
	v_cvt_pk_bf16_f32 v195, v196, v197
	global_store_dwordx2 v[102:103], v[194:195], off offset:16
	s_waitcnt vmcnt(15)
; #define GAS __attribute__((address_space(1)))
; __device__ __forceinline__ unsigned pk2(float lo, float hi) { const f32x2cv v = {lo, hi}; return __builtin_bit_cast(unsigned, __builtin_convertvector(v, bf16x2cv)); }
; __device__ __forceinline__ float gelu_tanh(float x) { const float u = 0.7978845608028654f * (x + 0.044715f * x * x * x); return x * __builtin_amdgcn_rcpf(1.0f + __builtin_amdgcn_exp2f(-2.8853900817779268f * u)); }
; __device__ __forceinline__ void ph_s5_out(Frame& F) {
;     ...
;                 for (int k = 0; k < 4; ++k) { const int tloc = 2 * (wave + 8 * i) + (k >> 1), p0 = 8 * (k & 1) + 4 * hh; const size_t m = (size_t)chunk * 64 + tloc;
;                     const v2u uw = *(const GAS v2u*)((chunk < 256 ? (const bf16*)(ws + WS_UG) : (const bf16*)(ws + WS_UGC)) + ug_index(g, (int)m, p0));
;                     const float y0 = gelu_tanh(acc[i][4 * k] + dsk[p0] * bflo(uw.x)), y1 = gelu_tanh(acc[i][4 * k + 1] + dsk[p0 + 1] * bfhi(uw.x));
;                     const float y2 = gelu_tanh(acc[i][4 * k + 2] + dsk[p0 + 2] * bflo(uw.y)), y3 = gelu_tanh(acc[i][4 * k + 3] + dsk[p0 + 3] * bfhi(uw.y));
;                     v2u zw; zw.x = pk2(y0, y1); zw.y = pk2(y2, y3);
;                     *(GAS v2u*)((bf16*)(ws + WS_Z) + m * 512 + 16 * g + p0) = zw; }
	v_lshlrev_b32_e32 v182, 16, v146
	v_and_b32_e32 v183, 0xffff0000, v146
	v_lshlrev_b32_e32 v184, 16, v147
	v_and_b32_e32 v185, 0xffff0000, v147
	v_pk_fma_f32 v[194:195], v[174:175], v[182:183], v[58:59]
	v_pk_fma_f32 v[196:197], v[176:177], v[184:185], v[60:61]
	v_mul_f32_e32 v190, 0x3d372713, v194
	v_mul_f32_e32 v191, 0x3d372713, v195
	v_mul_f32_e32 v192, 0x3d372713, v196
	v_mul_f32_e32 v193, 0x3d372713, v197
	v_mul_f32_e32 v190, v194, v190
	v_mul_f32_e32 v191, v195, v191
	v_mul_f32_e32 v192, v196, v192
	v_mul_f32_e32 v193, v197, v193
	v_fma_f32 v190, v194, v190, v194
	v_fma_f32 v191, v195, v191, v195
	v_fma_f32 v192, v196, v192, v196
	v_fma_f32 v193, v197, v193, v197
	v_mul_f32_e32 v190, 0x3f4c422a, v190
	v_mul_f32_e32 v191, 0x3f4c422a, v191
	v_mul_f32_e32 v192, 0x3f4c422a, v192
	v_mul_f32_e32 v193, 0x3f4c422a, v193
	v_mul_f32_e32 v190, 0xc038aa3b, v190
	v_mul_f32_e32 v191, 0xc038aa3b, v191
	v_mul_f32_e32 v192, 0xc038aa3b, v192
	v_mul_f32_e32 v193, 0xc038aa3b, v193
	v_exp_f32_e32 v190, v190
	v_exp_f32_e32 v191, v191
	v_exp_f32_e32 v192, v192
	v_exp_f32_e32 v193, v193
	v_add_f32_e32 v190, 1.0, v190
	v_add_f32_e32 v191, 1.0, v191
	v_add_f32_e32 v192, 1.0, v192
	v_add_f32_e32 v193, 1.0, v193
	v_rcp_f32_e32 v190, v190
	v_rcp_f32_e32 v191, v191
	v_rcp_f32_e32 v192, v192
	v_rcp_f32_e32 v193, v193
	v_pk_mul_f32 v[194:195], v[194:195], v[190:191]
	v_pk_mul_f32 v[196:197], v[196:197], v[192:193]
	v_cvt_pk_bf16_f32 v194, v194, v195
	v_cvt_pk_bf16_f32 v195, v196, v197
	global_store_dwordx2 v[102:103], v[194:195], off offset:1024
	s_waitcnt vmcnt(15)
	v_lshlrev_b32_e32 v182, 16, v148
	v_and_b32_e32 v183, 0xffff0000, v148
	v_lshlrev_b32_e32 v184, 16, v149
	v_and_b32_e32 v185, 0xffff0000, v149
	v_pk_fma_f32 v[194:195], v[178:179], v[182:183], v[62:63]
	v_pk_fma_f32 v[196:197], v[180:181], v[184:185], v[64:65]
	v_mul_f32_e32 v190, 0x3d372713, v194
	v_mul_f32_e32 v191, 0x3d372713, v195
	v_mul_f32_e32 v192, 0x3d372713, v196
	v_mul_f32_e32 v193, 0x3d372713, v197
	v_mul_f32_e32 v190, v194, v190
	v_mul_f32_e32 v191, v195, v191
	v_mul_f32_e32 v192, v196, v192
	v_mul_f32_e32 v193, v197, v193
	v_fma_f32 v190, v194, v190, v194
	v_fma_f32 v191, v195, v191, v195
	v_fma_f32 v192, v196, v192, v196
	v_fma_f32 v193, v197, v193, v197
	v_mul_f32_e32 v190, 0x3f4c422a, v190
	v_mul_f32_e32 v191, 0x3f4c422a, v191
	v_mul_f32_e32 v192, 0x3f4c422a, v192
	v_mul_f32_e32 v193, 0x3f4c422a, v193
	v_mul_f32_e32 v190, 0xc038aa3b, v190
	v_mul_f32_e32 v191, 0xc038aa3b, v191
	v_mul_f32_e32 v192, 0xc038aa3b, v192
	v_mul_f32_e32 v193, 0xc038aa3b, v193
	v_exp_f32_e32 v190, v190
	v_exp_f32_e32 v191, v191
	v_exp_f32_e32 v192, v192
	v_exp_f32_e32 v193, v193
	v_add_f32_e32 v190, 1.0, v190
	v_add_f32_e32 v191, 1.0, v191
	v_add_f32_e32 v192, 1.0, v192
	v_add_f32_e32 v193, 1.0, v193
	v_rcp_f32_e32 v190, v190
	v_rcp_f32_e32 v191, v191
	v_rcp_f32_e32 v192, v192
	v_rcp_f32_e32 v193, v193
	v_pk_mul_f32 v[194:195], v[194:195], v[190:191]
	v_pk_mul_f32 v[196:197], v[196:197], v[192:193]
	v_cvt_pk_bf16_f32 v194, v194, v195
	v_cvt_pk_bf16_f32 v195, v196, v197
	global_store_dwordx2 v[102:103], v[194:195], off offset:1040
	v_lshl_add_u64 v[102:103], v[102:103], 0, s[22:23]
	s_waitcnt vmcnt(15)
	v_lshlrev_b32_e32 v182, 16, v150
	v_and_b32_e32 v183, 0xffff0000, v150
	v_lshlrev_b32_e32 v184, 16, v151
	v_and_b32_e32 v185, 0xffff0000, v151
	v_pk_fma_f32 v[194:195], v[174:175], v[182:183], v[34:35]
	v_pk_fma_f32 v[196:197], v[176:177], v[184:185], v[36:37]
	v_mul_f32_e32 v190, 0x3d372713, v194
	v_mul_f32_e32 v191, 0x3d372713, v195
	v_mul_f32_e32 v192, 0x3d372713, v196
	v_mul_f32_e32 v193, 0x3d372713, v197
	v_mul_f32_e32 v190, v194, v190
	v_mul_f32_e32 v191, v195, v191
	v_mul_f32_e32 v192, v196, v192
	v_mul_f32_e32 v193, v197, v193
	v_fma_f32 v190, v194, v190, v194
	v_fma_f32 v191, v195, v191, v195
	v_fma_f32 v192, v196, v192, v196
	v_fma_f32 v193, v197, v193, v197
	v_mul_f32_e32 v190, 0x3f4c422a, v190
	v_mul_f32_e32 v191, 0x3f4c422a, v191
	v_mul_f32_e32 v192, 0x3f4c422a, v192
	v_mul_f32_e32 v193, 0x3f4c422a, v193
	v_mul_f32_e32 v190, 0xc038aa3b, v190
	v_mul_f32_e32 v191, 0xc038aa3b, v191
	v_mul_f32_e32 v192, 0xc038aa3b, v192
	v_mul_f32_e32 v193, 0xc038aa3b, v193
	v_exp_f32_e32 v190, v190
	v_exp_f32_e32 v191, v191
	v_exp_f32_e32 v192, v192
	v_exp_f32_e32 v193, v193
	v_add_f32_e32 v190, 1.0, v190
	v_add_f32_e32 v191, 1.0, v191
	v_add_f32_e32 v192, 1.0, v192
	v_add_f32_e32 v193, 1.0, v193
	v_rcp_f32_e32 v190, v190
	v_rcp_f32_e32 v191, v191
	v_rcp_f32_e32 v192, v192
	v_rcp_f32_e32 v193, v193
	v_pk_mul_f32 v[194:195], v[194:195], v[190:191]
	v_pk_mul_f32 v[196:197], v[196:197], v[192:193]
	v_cvt_pk_bf16_f32 v194, v194, v195
	v_cvt_pk_bf16_f32 v195, v196, v197
	global_store_dwordx2 v[102:103], v[194:195], off
	s_waitcnt vmcnt(15)
	v_lshlrev_b32_e32 v182, 16, v152
	v_and_b32_e32 v183, 0xffff0000, v152
	v_lshlrev_b32_e32 v184, 16, v153
	v_and_b32_e32 v185, 0xffff0000, v153
	v_pk_fma_f32 v[194:195], v[178:179], v[182:183], v[38:39]
	v_pk_fma_f32 v[196:197], v[180:181], v[184:185], v[40:41]
	v_mul_f32_e32 v190, 0x3d372713, v194
	v_mul_f32_e32 v191, 0x3d372713, v195
	v_mul_f32_e32 v192, 0x3d372713, v196
	v_mul_f32_e32 v193, 0x3d372713, v197
	v_mul_f32_e32 v190, v194, v190
	v_mul_f32_e32 v191, v195, v191
	v_mul_f32_e32 v192, v196, v192
	v_mul_f32_e32 v193, v197, v193
	v_fma_f32 v190, v194, v190, v194
	v_fma_f32 v191, v195, v191, v195
	v_fma_f32 v192, v196, v192, v196
	v_fma_f32 v193, v197, v193, v197
	v_mul_f32_e32 v190, 0x3f4c422a, v190
	v_mul_f32_e32 v191, 0x3f4c422a, v191
	v_mul_f32_e32 v192, 0x3f4c422a, v192
	v_mul_f32_e32 v193, 0x3f4c422a, v193
	v_mul_f32_e32 v190, 0xc038aa3b, v190
	v_mul_f32_e32 v191, 0xc038aa3b, v191
	v_mul_f32_e32 v192, 0xc038aa3b, v192
	v_mul_f32_e32 v193, 0xc038aa3b, v193
	v_exp_f32_e32 v190, v190
	v_exp_f32_e32 v191, v191
	v_exp_f32_e32 v192, v192
	v_exp_f32_e32 v193, v193
	v_add_f32_e32 v190, 1.0, v190
	v_add_f32_e32 v191, 1.0, v191
	v_add_f32_e32 v192, 1.0, v192
	v_add_f32_e32 v193, 1.0, v193
	v_rcp_f32_e32 v190, v190
	v_rcp_f32_e32 v191, v191
	v_rcp_f32_e32 v192, v192
	v_rcp_f32_e32 v193, v193
	v_pk_mul_f32 v[194:195], v[194:195], v[190:191]
	v_pk_mul_f32 v[196:197], v[196:197], v[192:193]
	v_cvt_pk_bf16_f32 v194, v194, v195
	v_cvt_pk_bf16_f32 v195, v196, v197
	global_store_dwordx2 v[102:103], v[194:195], off offset:16
	s_waitcnt vmcnt(15)
; #define GAS __attribute__((address_space(1)))
; __device__ __forceinline__ unsigned pk2(float lo, float hi) { const f32x2cv v = {lo, hi}; return __builtin_bit_cast(unsigned, __builtin_convertvector(v, bf16x2cv)); }
; __device__ __forceinline__ float gelu_tanh(float x) { const float u = 0.7978845608028654f * (x + 0.044715f * x * x * x); return x * __builtin_amdgcn_rcpf(1.0f + __builtin_amdgcn_exp2f(-2.8853900817779268f * u)); }
; __device__ __forceinline__ void ph_s5_out(Frame& F) {
;     ...
;                 for (int k = 0; k < 4; ++k) { const int tloc = 2 * (wave + 8 * i) + (k >> 1), p0 = 8 * (k & 1) + 4 * hh; const size_t m = (size_t)chunk * 64 + tloc;
;                     const v2u uw = *(const GAS v2u*)((chunk < 256 ? (const bf16*)(ws + WS_UG) : (const bf16*)(ws + WS_UGC)) + ug_index(g, (int)m, p0));
;                     const float y0 = gelu_tanh(acc[i][4 * k] + dsk[p0] * bflo(uw.x)), y1 = gelu_tanh(acc[i][4 * k + 1] + dsk[p0 + 1] * bfhi(uw.x));
;                     const float y2 = gelu_tanh(acc[i][4 * k + 2] + dsk[p0 + 2] * bflo(uw.y)), y3 = gelu_tanh(acc[i][4 * k + 3] + dsk[p0 + 3] * bfhi(uw.y));
;                     v2u zw; zw.x = pk2(y0, y1); zw.y = pk2(y2, y3);
;                     *(GAS v2u*)((bf16*)(ws + WS_Z) + m * 512 + 16 * g + p0) = zw; }
	v_lshlrev_b32_e32 v182, 16, v154
	v_and_b32_e32 v183, 0xffff0000, v154
	v_lshlrev_b32_e32 v184, 16, v155
	v_and_b32_e32 v185, 0xffff0000, v155
	v_pk_fma_f32 v[194:195], v[174:175], v[182:183], v[42:43]
	v_pk_fma_f32 v[196:197], v[176:177], v[184:185], v[44:45]
	v_mul_f32_e32 v190, 0x3d372713, v194
	v_mul_f32_e32 v191, 0x3d372713, v195
	v_mul_f32_e32 v192, 0x3d372713, v196
	v_mul_f32_e32 v193, 0x3d372713, v197
	v_mul_f32_e32 v190, v194, v190
	v_mul_f32_e32 v191, v195, v191
	v_mul_f32_e32 v192, v196, v192
	v_mul_f32_e32 v193, v197, v193
	v_fma_f32 v190, v194, v190, v194
	v_fma_f32 v191, v195, v191, v195
	v_fma_f32 v192, v196, v192, v196
	v_fma_f32 v193, v197, v193, v197
	v_mul_f32_e32 v190, 0x3f4c422a, v190
	v_mul_f32_e32 v191, 0x3f4c422a, v191
	v_mul_f32_e32 v192, 0x3f4c422a, v192
	v_mul_f32_e32 v193, 0x3f4c422a, v193
	v_mul_f32_e32 v190, 0xc038aa3b, v190
	v_mul_f32_e32 v191, 0xc038aa3b, v191
	v_mul_f32_e32 v192, 0xc038aa3b, v192
	v_mul_f32_e32 v193, 0xc038aa3b, v193
	v_exp_f32_e32 v190, v190
	v_exp_f32_e32 v191, v191
	v_exp_f32_e32 v192, v192
	v_exp_f32_e32 v193, v193
	v_add_f32_e32 v190, 1.0, v190
	v_add_f32_e32 v191, 1.0, v191
	v_add_f32_e32 v192, 1.0, v192
	v_add_f32_e32 v193, 1.0, v193
	v_rcp_f32_e32 v190, v190
	v_rcp_f32_e32 v191, v191
	v_rcp_f32_e32 v192, v192
	v_rcp_f32_e32 v193, v193
	v_pk_mul_f32 v[194:195], v[194:195], v[190:191]
	v_pk_mul_f32 v[196:197], v[196:197], v[192:193]
	v_cvt_pk_bf16_f32 v194, v194, v195
	v_cvt_pk_bf16_f32 v195, v196, v197
	global_store_dwordx2 v[102:103], v[194:195], off offset:1024
	s_waitcnt vmcnt(15)
	v_lshlrev_b32_e32 v182, 16, v156
	v_and_b32_e32 v183, 0xffff0000, v156
	v_lshlrev_b32_e32 v184, 16, v157
	v_and_b32_e32 v185, 0xffff0000, v157
	v_pk_fma_f32 v[194:195], v[178:179], v[182:183], v[46:47]
	v_pk_fma_f32 v[196:197], v[180:181], v[184:185], v[48:49]
	v_mul_f32_e32 v190, 0x3d372713, v194
	v_mul_f32_e32 v191, 0x3d372713, v195
	v_mul_f32_e32 v192, 0x3d372713, v196
	v_mul_f32_e32 v193, 0x3d372713, v197
	v_mul_f32_e32 v190, v194, v190
	v_mul_f32_e32 v191, v195, v191
	v_mul_f32_e32 v192, v196, v192
	v_mul_f32_e32 v193, v197, v193
	v_fma_f32 v190, v194, v190, v194
	v_fma_f32 v191, v195, v191, v195
	v_fma_f32 v192, v196, v192, v196
	v_fma_f32 v193, v197, v193, v197
	v_mul_f32_e32 v190, 0x3f4c422a, v190
	v_mul_f32_e32 v191, 0x3f4c422a, v191
	v_mul_f32_e32 v192, 0x3f4c422a, v192
	v_mul_f32_e32 v193, 0x3f4c422a, v193
	v_mul_f32_e32 v190, 0xc038aa3b, v190
	v_mul_f32_e32 v191, 0xc038aa3b, v191
	v_mul_f32_e32 v192, 0xc038aa3b, v192
	v_mul_f32_e32 v193, 0xc038aa3b, v193
	v_exp_f32_e32 v190, v190
	v_exp_f32_e32 v191, v191
	v_exp_f32_e32 v192, v192
	v_exp_f32_e32 v193, v193
	v_add_f32_e32 v190, 1.0, v190
	v_add_f32_e32 v191, 1.0, v191
	v_add_f32_e32 v192, 1.0, v192
	v_add_f32_e32 v193, 1.0, v193
	v_rcp_f32_e32 v190, v190
	v_rcp_f32_e32 v191, v191
	v_rcp_f32_e32 v192, v192
	v_rcp_f32_e32 v193, v193
	v_pk_mul_f32 v[194:195], v[194:195], v[190:191]
	v_pk_mul_f32 v[196:197], v[196:197], v[192:193]
	v_cvt_pk_bf16_f32 v194, v194, v195
	v_cvt_pk_bf16_f32 v195, v196, v197
	global_store_dwordx2 v[102:103], v[194:195], off offset:1040
	v_lshl_add_u64 v[102:103], v[102:103], 0, s[22:23]
	s_waitcnt vmcnt(15)
	v_lshlrev_b32_e32 v182, 16, v158
	v_and_b32_e32 v183, 0xffff0000, v158
	v_lshlrev_b32_e32 v184, 16, v159
	v_and_b32_e32 v185, 0xffff0000, v159
	v_pk_fma_f32 v[194:195], v[174:175], v[182:183], v[18:19]
	v_pk_fma_f32 v[196:197], v[176:177], v[184:185], v[20:21]
	v_mul_f32_e32 v190, 0x3d372713, v194
	v_mul_f32_e32 v191, 0x3d372713, v195
	v_mul_f32_e32 v192, 0x3d372713, v196
	v_mul_f32_e32 v193, 0x3d372713, v197
	v_mul_f32_e32 v190, v194, v190
	v_mul_f32_e32 v191, v195, v191
	v_mul_f32_e32 v192, v196, v192
	v_mul_f32_e32 v193, v197, v193
	v_fma_f32 v190, v194, v190, v194
	v_fma_f32 v191, v195, v191, v195
	v_fma_f32 v192, v196, v192, v196
	v_fma_f32 v193, v197, v193, v197
	v_mul_f32_e32 v190, 0x3f4c422a, v190
	v_mul_f32_e32 v191, 0x3f4c422a, v191
	v_mul_f32_e32 v192, 0x3f4c422a, v192
	v_mul_f32_e32 v193, 0x3f4c422a, v193
	v_mul_f32_e32 v190, 0xc038aa3b, v190
	v_mul_f32_e32 v191, 0xc038aa3b, v191
	v_mul_f32_e32 v192, 0xc038aa3b, v192
	v_mul_f32_e32 v193, 0xc038aa3b, v193
	v_exp_f32_e32 v190, v190
	v_exp_f32_e32 v191, v191
	v_exp_f32_e32 v192, v192
	v_exp_f32_e32 v193, v193
	v_add_f32_e32 v190, 1.0, v190
	v_add_f32_e32 v191, 1.0, v191
	v_add_f32_e32 v192, 1.0, v192
	v_add_f32_e32 v193, 1.0, v193
	v_rcp_f32_e32 v190, v190
	v_rcp_f32_e32 v191, v191
	v_rcp_f32_e32 v192, v192
	v_rcp_f32_e32 v193, v193
	v_pk_mul_f32 v[194:195], v[194:195], v[190:191]
	v_pk_mul_f32 v[196:197], v[196:197], v[192:193]
	v_cvt_pk_bf16_f32 v194, v194, v195
	v_cvt_pk_bf16_f32 v195, v196, v197
	global_store_dwordx2 v[102:103], v[194:195], off
	s_waitcnt vmcnt(15)
	v_lshlrev_b32_e32 v182, 16, v160
	v_and_b32_e32 v183, 0xffff0000, v160
	v_lshlrev_b32_e32 v184, 16, v161
	v_and_b32_e32 v185, 0xffff0000, v161
	v_pk_fma_f32 v[194:195], v[178:179], v[182:183], v[22:23]
	v_pk_fma_f32 v[196:197], v[180:181], v[184:185], v[24:25]
	v_mul_f32_e32 v190, 0x3d372713, v194
	v_mul_f32_e32 v191, 0x3d372713, v195
	v_mul_f32_e32 v192, 0x3d372713, v196
	v_mul_f32_e32 v193, 0x3d372713, v197
	v_mul_f32_e32 v190, v194, v190
	v_mul_f32_e32 v191, v195, v191
	v_mul_f32_e32 v192, v196, v192
	v_mul_f32_e32 v193, v197, v193
	v_fma_f32 v190, v194, v190, v194
	v_fma_f32 v191, v195, v191, v195
	v_fma_f32 v192, v196, v192, v196
	v_fma_f32 v193, v197, v193, v197
	v_mul_f32_e32 v190, 0x3f4c422a, v190
	v_mul_f32_e32 v191, 0x3f4c422a, v191
	v_mul_f32_e32 v192, 0x3f4c422a, v192
	v_mul_f32_e32 v193, 0x3f4c422a, v193
	v_mul_f32_e32 v190, 0xc038aa3b, v190
	v_mul_f32_e32 v191, 0xc038aa3b, v191
	v_mul_f32_e32 v192, 0xc038aa3b, v192
	v_mul_f32_e32 v193, 0xc038aa3b, v193
	v_exp_f32_e32 v190, v190
	v_exp_f32_e32 v191, v191
	v_exp_f32_e32 v192, v192
	v_exp_f32_e32 v193, v193
	v_add_f32_e32 v190, 1.0, v190
	v_add_f32_e32 v191, 1.0, v191
	v_add_f32_e32 v192, 1.0, v192
	v_add_f32_e32 v193, 1.0, v193
	v_rcp_f32_e32 v190, v190
	v_rcp_f32_e32 v191, v191
	v_rcp_f32_e32 v192, v192
	v_rcp_f32_e32 v193, v193
	v_pk_mul_f32 v[194:195], v[194:195], v[190:191]
	v_pk_mul_f32 v[196:197], v[196:197], v[192:193]
	v_cvt_pk_bf16_f32 v194, v194, v195
	v_cvt_pk_bf16_f32 v195, v196, v197
	global_store_dwordx2 v[102:103], v[194:195], off offset:16
	s_waitcnt vmcnt(15)
; #define GAS __attribute__((address_space(1)))
; __device__ __forceinline__ unsigned pk2(float lo, float hi) { const f32x2cv v = {lo, hi}; return __builtin_bit_cast(unsigned, __builtin_convertvector(v, bf16x2cv)); }
; __device__ __forceinline__ float gelu_tanh(float x) { const float u = 0.7978845608028654f * (x + 0.044715f * x * x * x); return x * __builtin_amdgcn_rcpf(1.0f + __builtin_amdgcn_exp2f(-2.8853900817779268f * u)); }
; __device__ __forceinline__ void ph_s5_out(Frame& F) {
;     ...
;                 for (int k = 0; k < 4; ++k) { const int tloc = 2 * (wave + 8 * i) + (k >> 1), p0 = 8 * (k & 1) + 4 * hh; const size_t m = (size_t)chunk * 64 + tloc;
;                     const v2u uw = *(const GAS v2u*)((chunk < 256 ? (const bf16*)(ws + WS_UG) : (const bf16*)(ws + WS_UGC)) + ug_index(g, (int)m, p0));
;                     const float y0 = gelu_tanh(acc[i][4 * k] + dsk[p0] * bflo(uw.x)), y1 = gelu_tanh(acc[i][4 * k + 1] + dsk[p0 + 1] * bfhi(uw.x));
;                     const float y2 = gelu_tanh(acc[i][4 * k + 2] + dsk[p0 + 2] * bflo(uw.y)), y3 = gelu_tanh(acc[i][4 * k + 3] + dsk[p0 + 3] * bfhi(uw.y));
;                     v2u zw; zw.x = pk2(y0, y1); zw.y = pk2(y2, y3);
;                     *(GAS v2u*)((bf16*)(ws + WS_Z) + m * 512 + 16 * g + p0) = zw; }
	v_lshlrev_b32_e32 v182, 16, v162
	v_and_b32_e32 v183, 0xffff0000, v162
	v_lshlrev_b32_e32 v184, 16, v163
	v_and_b32_e32 v185, 0xffff0000, v163
	v_pk_fma_f32 v[194:195], v[174:175], v[182:183], v[26:27]
	v_pk_fma_f32 v[196:197], v[176:177], v[184:185], v[28:29]
	v_mul_f32_e32 v190, 0x3d372713, v194
	v_mul_f32_e32 v191, 0x3d372713, v195
	v_mul_f32_e32 v192, 0x3d372713, v196
	v_mul_f32_e32 v193, 0x3d372713, v197
	v_mul_f32_e32 v190, v194, v190
	v_mul_f32_e32 v191, v195, v191
	v_mul_f32_e32 v192, v196, v192
	v_mul_f32_e32 v193, v197, v193
	v_fma_f32 v190, v194, v190, v194
	v_fma_f32 v191, v195, v191, v195
	v_fma_f32 v192, v196, v192, v196
	v_fma_f32 v193, v197, v193, v197
	v_mul_f32_e32 v190, 0x3f4c422a, v190
	v_mul_f32_e32 v191, 0x3f4c422a, v191
	v_mul_f32_e32 v192, 0x3f4c422a, v192
	v_mul_f32_e32 v193, 0x3f4c422a, v193
	v_mul_f32_e32 v190, 0xc038aa3b, v190
	v_mul_f32_e32 v191, 0xc038aa3b, v191
	v_mul_f32_e32 v192, 0xc038aa3b, v192
	v_mul_f32_e32 v193, 0xc038aa3b, v193
	v_exp_f32_e32 v190, v190
	v_exp_f32_e32 v191, v191
	v_exp_f32_e32 v192, v192
	v_exp_f32_e32 v193, v193
	v_add_f32_e32 v190, 1.0, v190
	v_add_f32_e32 v191, 1.0, v191
	v_add_f32_e32 v192, 1.0, v192
	v_add_f32_e32 v193, 1.0, v193
	v_rcp_f32_e32 v190, v190
	v_rcp_f32_e32 v191, v191
	v_rcp_f32_e32 v192, v192
	v_rcp_f32_e32 v193, v193
	v_pk_mul_f32 v[194:195], v[194:195], v[190:191]
	v_pk_mul_f32 v[196:197], v[196:197], v[192:193]
	v_cvt_pk_bf16_f32 v194, v194, v195
	v_cvt_pk_bf16_f32 v195, v196, v197
	global_store_dwordx2 v[102:103], v[194:195], off offset:1024
	s_waitcnt vmcnt(15)
	v_lshlrev_b32_e32 v182, 16, v164
	v_and_b32_e32 v183, 0xffff0000, v164
	v_lshlrev_b32_e32 v184, 16, v165
	v_and_b32_e32 v185, 0xffff0000, v165
	v_pk_fma_f32 v[194:195], v[178:179], v[182:183], v[30:31]
	v_pk_fma_f32 v[196:197], v[180:181], v[184:185], v[32:33]
	v_mul_f32_e32 v190, 0x3d372713, v194
	v_mul_f32_e32 v191, 0x3d372713, v195
	v_mul_f32_e32 v192, 0x3d372713, v196
	v_mul_f32_e32 v193, 0x3d372713, v197
	v_mul_f32_e32 v190, v194, v190
	v_mul_f32_e32 v191, v195, v191
	v_mul_f32_e32 v192, v196, v192
	v_mul_f32_e32 v193, v197, v193
	v_fma_f32 v190, v194, v190, v194
	v_fma_f32 v191, v195, v191, v195
	v_fma_f32 v192, v196, v192, v196
	v_fma_f32 v193, v197, v193, v197
	v_mul_f32_e32 v190, 0x3f4c422a, v190
	v_mul_f32_e32 v191, 0x3f4c422a, v191
	v_mul_f32_e32 v192, 0x3f4c422a, v192
	v_mul_f32_e32 v193, 0x3f4c422a, v193
	v_mul_f32_e32 v190, 0xc038aa3b, v190
	v_mul_f32_e32 v191, 0xc038aa3b, v191
	v_mul_f32_e32 v192, 0xc038aa3b, v192
	v_mul_f32_e32 v193, 0xc038aa3b, v193
	v_exp_f32_e32 v190, v190
	v_exp_f32_e32 v191, v191
	v_exp_f32_e32 v192, v192
	v_exp_f32_e32 v193, v193
	v_add_f32_e32 v190, 1.0, v190
	v_add_f32_e32 v191, 1.0, v191
	v_add_f32_e32 v192, 1.0, v192
	v_add_f32_e32 v193, 1.0, v193
	v_rcp_f32_e32 v190, v190
	v_rcp_f32_e32 v191, v191
	v_rcp_f32_e32 v192, v192
	v_rcp_f32_e32 v193, v193
	v_pk_mul_f32 v[194:195], v[194:195], v[190:191]
	v_pk_mul_f32 v[196:197], v[196:197], v[192:193]
	v_cvt_pk_bf16_f32 v194, v194, v195
	v_cvt_pk_bf16_f32 v195, v196, v197
	global_store_dwordx2 v[102:103], v[194:195], off offset:1040
	v_lshl_add_u64 v[102:103], v[102:103], 0, s[22:23]
	s_waitcnt vmcnt(15)
	v_lshlrev_b32_e32 v182, 16, v166
	v_and_b32_e32 v183, 0xffff0000, v166
	v_lshlrev_b32_e32 v184, 16, v167
	v_and_b32_e32 v185, 0xffff0000, v167
	v_pk_fma_f32 v[194:195], v[174:175], v[182:183], v[2:3]
	v_pk_fma_f32 v[196:197], v[176:177], v[184:185], v[4:5]
	v_mul_f32_e32 v190, 0x3d372713, v194
	v_mul_f32_e32 v191, 0x3d372713, v195
	v_mul_f32_e32 v192, 0x3d372713, v196
	v_mul_f32_e32 v193, 0x3d372713, v197
	v_mul_f32_e32 v190, v194, v190
	v_mul_f32_e32 v191, v195, v191
	v_mul_f32_e32 v192, v196, v192
	v_mul_f32_e32 v193, v197, v193
	v_fma_f32 v190, v194, v190, v194
	v_fma_f32 v191, v195, v191, v195
	v_fma_f32 v192, v196, v192, v196
	v_fma_f32 v193, v197, v193, v197
	v_mul_f32_e32 v190, 0x3f4c422a, v190
	v_mul_f32_e32 v191, 0x3f4c422a, v191
	v_mul_f32_e32 v192, 0x3f4c422a, v192
	v_mul_f32_e32 v193, 0x3f4c422a, v193
	v_mul_f32_e32 v190, 0xc038aa3b, v190
	v_mul_f32_e32 v191, 0xc038aa3b, v191
	v_mul_f32_e32 v192, 0xc038aa3b, v192
	v_mul_f32_e32 v193, 0xc038aa3b, v193
	v_exp_f32_e32 v190, v190
	v_exp_f32_e32 v191, v191
	v_exp_f32_e32 v192, v192
	v_exp_f32_e32 v193, v193
	v_add_f32_e32 v190, 1.0, v190
	v_add_f32_e32 v191, 1.0, v191
	v_add_f32_e32 v192, 1.0, v192
	v_add_f32_e32 v193, 1.0, v193
	v_rcp_f32_e32 v190, v190
	v_rcp_f32_e32 v191, v191
	v_rcp_f32_e32 v192, v192
	v_rcp_f32_e32 v193, v193
	v_pk_mul_f32 v[194:195], v[194:195], v[190:191]
	v_pk_mul_f32 v[196:197], v[196:197], v[192:193]
	v_cvt_pk_bf16_f32 v194, v194, v195
	v_cvt_pk_bf16_f32 v195, v196, v197
	global_store_dwordx2 v[102:103], v[194:195], off
	s_waitcnt vmcnt(15)
; #define GAS __attribute__((address_space(1)))
; __device__ __forceinline__ unsigned pk2(float lo, float hi) { const f32x2cv v = {lo, hi}; return __builtin_bit_cast(unsigned, __builtin_convertvector(v, bf16x2cv)); }
; __device__ __forceinline__ float gelu_tanh(float x) { const float u = 0.7978845608028654f * (x + 0.044715f * x * x * x); return x * __builtin_amdgcn_rcpf(1.0f + __builtin_amdgcn_exp2f(-2.8853900817779268f * u)); }
; __device__ __forceinline__ void ph_s5_out(Frame& F) {
;     ...
;                 for (int k = 0; k < 4; ++k) { const int tloc = 2 * (wave + 8 * i) + (k >> 1), p0 = 8 * (k & 1) + 4 * hh; const size_t m = (size_t)chunk * 64 + tloc;
;                     const v2u uw = *(const GAS v2u*)((chunk < 256 ? (const bf16*)(ws + WS_UG) : (const bf16*)(ws + WS_UGC)) + ug_index(g, (int)m, p0));
;                     const float y0 = gelu_tanh(acc[i][4 * k] + dsk[p0] * bflo(uw.x)), y1 = gelu_tanh(acc[i][4 * k + 1] + dsk[p0 + 1] * bfhi(uw.x));
;                     const float y2 = gelu_tanh(acc[i][4 * k + 2] + dsk[p0 + 2] * bflo(uw.y)), y3 = gelu_tanh(acc[i][4 * k + 3] + dsk[p0 + 3] * bfhi(uw.y));
;                     v2u zw; zw.x = pk2(y0, y1); zw.y = pk2(y2, y3);
;                     *(GAS v2u*)((bf16*)(ws + WS_Z) + m * 512 + 16 * g + p0) = zw; }
	v_lshlrev_b32_e32 v182, 16, v168
	v_and_b32_e32 v183, 0xffff0000, v168
	v_lshlrev_b32_e32 v184, 16, v169
	v_and_b32_e32 v185, 0xffff0000, v169
	v_pk_fma_f32 v[194:195], v[178:179], v[182:183], v[6:7]
	v_pk_fma_f32 v[196:197], v[180:181], v[184:185], v[8:9]
	v_mul_f32_e32 v190, 0x3d372713, v194
	v_mul_f32_e32 v191, 0x3d372713, v195
	v_mul_f32_e32 v192, 0x3d372713, v196
	v_mul_f32_e32 v193, 0x3d372713, v197
	v_mul_f32_e32 v190, v194, v190
	v_mul_f32_e32 v191, v195, v191
	v_mul_f32_e32 v192, v196, v192
	v_mul_f32_e32 v193, v197, v193
	v_fma_f32 v190, v194, v190, v194
	v_fma_f32 v191, v195, v191, v195
	v_fma_f32 v192, v196, v192, v196
	v_fma_f32 v193, v197, v193, v197
	v_mul_f32_e32 v190, 0x3f4c422a, v190
	v_mul_f32_e32 v191, 0x3f4c422a, v191
	v_mul_f32_e32 v192, 0x3f4c422a, v192
	v_mul_f32_e32 v193, 0x3f4c422a, v193
	v_mul_f32_e32 v190, 0xc038aa3b, v190
	v_mul_f32_e32 v191, 0xc038aa3b, v191
	v_mul_f32_e32 v192, 0xc038aa3b, v192
	v_mul_f32_e32 v193, 0xc038aa3b, v193
	v_exp_f32_e32 v190, v190
	v_exp_f32_e32 v191, v191
	v_exp_f32_e32 v192, v192
	v_exp_f32_e32 v193, v193
	v_add_f32_e32 v190, 1.0, v190
	v_add_f32_e32 v191, 1.0, v191
	v_add_f32_e32 v192, 1.0, v192
	v_add_f32_e32 v193, 1.0, v193
	v_rcp_f32_e32 v190, v190
	v_rcp_f32_e32 v191, v191
	v_rcp_f32_e32 v192, v192
	v_rcp_f32_e32 v193, v193
	v_pk_mul_f32 v[194:195], v[194:195], v[190:191]
	v_pk_mul_f32 v[196:197], v[196:197], v[192:193]
	v_cvt_pk_bf16_f32 v194, v194, v195
	v_cvt_pk_bf16_f32 v195, v196, v197
	global_store_dwordx2 v[102:103], v[194:195], off offset:16
	s_waitcnt vmcnt(15)
	v_lshlrev_b32_e32 v182, 16, v170
	v_and_b32_e32 v183, 0xffff0000, v170
	v_lshlrev_b32_e32 v184, 16, v171
	v_and_b32_e32 v185, 0xffff0000, v171
	v_pk_fma_f32 v[194:195], v[174:175], v[182:183], v[10:11]
	v_pk_fma_f32 v[196:197], v[176:177], v[184:185], v[12:13]
	v_mul_f32_e32 v190, 0x3d372713, v194
	v_mul_f32_e32 v191, 0x3d372713, v195
	v_mul_f32_e32 v192, 0x3d372713, v196
	v_mul_f32_e32 v193, 0x3d372713, v197
	v_mul_f32_e32 v190, v194, v190
	v_mul_f32_e32 v191, v195, v191
	v_mul_f32_e32 v192, v196, v192
	v_mul_f32_e32 v193, v197, v193
	v_fma_f32 v190, v194, v190, v194
	v_fma_f32 v191, v195, v191, v195
	v_fma_f32 v192, v196, v192, v196
	v_fma_f32 v193, v197, v193, v197
	v_mul_f32_e32 v190, 0x3f4c422a, v190
	v_mul_f32_e32 v191, 0x3f4c422a, v191
	v_mul_f32_e32 v192, 0x3f4c422a, v192
	v_mul_f32_e32 v193, 0x3f4c422a, v193
	v_mul_f32_e32 v190, 0xc038aa3b, v190
	v_mul_f32_e32 v191, 0xc038aa3b, v191
	v_mul_f32_e32 v192, 0xc038aa3b, v192
	v_mul_f32_e32 v193, 0xc038aa3b, v193
	v_exp_f32_e32 v190, v190
	v_exp_f32_e32 v191, v191
	v_exp_f32_e32 v192, v192
	v_exp_f32_e32 v193, v193
	v_add_f32_e32 v190, 1.0, v190
	v_add_f32_e32 v191, 1.0, v191
	v_add_f32_e32 v192, 1.0, v192
	v_add_f32_e32 v193, 1.0, v193
	v_rcp_f32_e32 v190, v190
	v_rcp_f32_e32 v191, v191
	v_rcp_f32_e32 v192, v192
	v_rcp_f32_e32 v193, v193
	v_pk_mul_f32 v[194:195], v[194:195], v[190:191]
	v_pk_mul_f32 v[196:197], v[196:197], v[192:193]
	v_cvt_pk_bf16_f32 v194, v194, v195
	v_cvt_pk_bf16_f32 v195, v196, v197
	global_store_dwordx2 v[102:103], v[194:195], off offset:1024
	s_waitcnt vmcnt(15)
	v_lshlrev_b32_e32 v182, 16, v172
	v_and_b32_e32 v183, 0xffff0000, v172
	v_lshlrev_b32_e32 v184, 16, v173
	v_and_b32_e32 v185, 0xffff0000, v173
	v_pk_fma_f32 v[194:195], v[178:179], v[182:183], v[14:15]
	v_pk_fma_f32 v[196:197], v[180:181], v[184:185], v[16:17]
	v_mul_f32_e32 v190, 0x3d372713, v194
	v_mul_f32_e32 v191, 0x3d372713, v195
	v_mul_f32_e32 v192, 0x3d372713, v196
	v_mul_f32_e32 v193, 0x3d372713, v197
	v_mul_f32_e32 v190, v194, v190
	v_mul_f32_e32 v191, v195, v191
	v_mul_f32_e32 v192, v196, v192
	v_mul_f32_e32 v193, v197, v193
	v_fma_f32 v190, v194, v190, v194
	v_fma_f32 v191, v195, v191, v195
	v_fma_f32 v192, v196, v192, v196
	v_fma_f32 v193, v197, v193, v197
	v_mul_f32_e32 v190, 0x3f4c422a, v190
	v_mul_f32_e32 v191, 0x3f4c422a, v191
	v_mul_f32_e32 v192, 0x3f4c422a, v192
	v_mul_f32_e32 v193, 0x3f4c422a, v193
	v_mul_f32_e32 v190, 0xc038aa3b, v190
	v_mul_f32_e32 v191, 0xc038aa3b, v191
	v_mul_f32_e32 v192, 0xc038aa3b, v192
	v_mul_f32_e32 v193, 0xc038aa3b, v193
	v_exp_f32_e32 v190, v190
	v_exp_f32_e32 v191, v191
	v_exp_f32_e32 v192, v192
	v_exp_f32_e32 v193, v193
	v_add_f32_e32 v190, 1.0, v190
	v_add_f32_e32 v191, 1.0, v191
	v_add_f32_e32 v192, 1.0, v192
	v_add_f32_e32 v193, 1.0, v193
	v_rcp_f32_e32 v190, v190
	v_rcp_f32_e32 v191, v191
	v_rcp_f32_e32 v192, v192
	v_rcp_f32_e32 v193, v193
	v_pk_mul_f32 v[194:195], v[194:195], v[190:191]
	v_pk_mul_f32 v[196:197], v[196:197], v[192:193]
	v_cvt_pk_bf16_f32 v194, v194, v195
	v_cvt_pk_bf16_f32 v195, v196, v197
	global_store_dwordx2 v[102:103], v[194:195], off offset:1040
	s_branch .LBB0_963
